# K-loop LDS-DMA loads: saddr form (SGPR base + 32-bit VGPR offset) at 27 sites, dropping the per-load 64-bit VALU address add
# baseline (speedup 1.0000x reference)
.Lkprio_5:
.LBB0_57:
	s_add_u32 s22, s0, 0xfffc0080
	s_addc_u32 s23, s1, -1
	s_add_i32 s65, 0, 0x10000
	v_add_u32_e32 v142, s65, v178
	ds_read_b128 v[130:133], v142
	ds_read_b128 v[134:137], v142 offset:1024
	ds_read_b128 v[138:141], v142 offset:2048
	ds_read_b128 v[142:145], v142 offset:3072
	s_cmp_eq_u32 s64, 12
	s_cselect_b32 s49, s37, s23
	s_cselect_b32 s48, s60, s22
	s_cselect_b32 s23, s35, s63
	s_cselect_b32 s22, s61, s62
	v_lshl_add_u64 v[186:187], s[0:1], 0, v[168:169]
	s_add_i32 m0, s47, 0xc000
	ds_read_b128 v[172:175], v180
	ds_read_b128 v[182:185], v180 offset:1024
	ds_read_b128 v[206:209], v180 offset:2048
	ds_read_b128 v[210:213], v180 offset:3072
	ds_read_b128 v[214:217], v180 offset:4096
	ds_read_b128 v[218:221], v180 offset:5120
	ds_read_b128 v[222:225], v180 offset:6144
	ds_read_b128 v[226:229], v180 offset:7168
	global_load_lds_dwordx4 v[186:187], off
	s_add_i32 m0, s47, 0xe000
	v_lshl_add_u64 v[186:187], s[0:1], 0, v[170:171]
	global_load_lds_dwordx4 v[186:187], off
	s_waitcnt lgkmcnt(8)
	s_barrier
	s_waitcnt lgkmcnt(0)
	v_mfma_f32_16x16x32_bf16 v[126:129], v[130:133], v[172:175], v[126:129]
	v_mfma_f32_16x16x32_bf16 v[122:125], v[138:141], v[172:175], v[122:125]
	v_mfma_f32_16x16x32_bf16 v[114:117], v[130:133], v[206:209], v[114:117]
	v_mfma_f32_16x16x32_bf16 v[106:109], v[138:141], v[206:209], v[106:109]
	v_mfma_f32_16x16x32_bf16 v[98:101], v[130:133], v[214:217], v[98:101]
	v_mfma_f32_16x16x32_bf16 v[90:93], v[138:141], v[214:217], v[90:93]
	v_mfma_f32_16x16x32_bf16 v[82:85], v[130:133], v[222:225], v[82:85]
	v_mfma_f32_16x16x32_bf16 v[74:77], v[138:141], v[222:225], v[74:77]
	v_mfma_f32_16x16x32_bf16 v[126:129], v[134:137], v[182:185], v[126:129]
	v_mfma_f32_16x16x32_bf16 v[122:125], v[142:145], v[182:185], v[122:125]
	v_mfma_f32_16x16x32_bf16 v[114:117], v[134:137], v[210:213], v[114:117]
	v_mfma_f32_16x16x32_bf16 v[106:109], v[142:145], v[210:213], v[106:109]
	v_mfma_f32_16x16x32_bf16 v[98:101], v[134:137], v[218:221], v[98:101]
	v_mfma_f32_16x16x32_bf16 v[90:93], v[142:145], v[218:221], v[90:93]
	v_mfma_f32_16x16x32_bf16 v[82:85], v[134:137], v[226:229], v[82:85]
	v_mfma_f32_16x16x32_bf16 v[74:77], v[142:145], v[226:229], v[74:77]
	s_barrier
	s_add_i32 s68, 0, 0x14000
	s_add_i32 s65, s65, s27
	v_add_u32_e32 v181, s68, v178
	v_lshl_add_u64 v[186:187], s[22:23], 0, v[0:1]
	s_mov_b32 m0, s65
	ds_read_b128 v[230:233], v181
	ds_read_b128 v[234:237], v181 offset:1024
	ds_read_b128 v[238:241], v181 offset:2048
	ds_read_b128 v[242:245], v181 offset:3072
	global_load_lds_dwordx4 v[186:187], off
	s_add_i32 m0, s65, 0x2000
	v_lshl_add_u64 v[246:247], s[22:23], 0, v[166:167]
	global_load_lds_dwordx4 v[246:247], off
	s_barrier
	s_waitcnt lgkmcnt(0)
	v_mfma_f32_16x16x32_bf16 v[118:121], v[230:233], v[172:175], v[118:121]
	v_mfma_f32_16x16x32_bf16 v[110:113], v[238:241], v[172:175], v[110:113]
	v_mfma_f32_16x16x32_bf16 v[102:105], v[230:233], v[206:209], v[102:105]
	v_mfma_f32_16x16x32_bf16 v[94:97], v[238:241], v[206:209], v[94:97]
	v_mfma_f32_16x16x32_bf16 v[86:89], v[230:233], v[214:217], v[86:89]
	v_mfma_f32_16x16x32_bf16 v[78:81], v[238:241], v[214:217], v[78:81]
	v_mfma_f32_16x16x32_bf16 v[70:73], v[230:233], v[222:225], v[70:73]
	v_mfma_f32_16x16x32_bf16 v[66:69], v[238:241], v[222:225], v[66:69]
	v_mfma_f32_16x16x32_bf16 v[118:121], v[234:237], v[182:185], v[118:121]
	v_mfma_f32_16x16x32_bf16 v[110:113], v[242:245], v[182:185], v[110:113]
	v_mfma_f32_16x16x32_bf16 v[102:105], v[234:237], v[210:213], v[102:105]
	v_mfma_f32_16x16x32_bf16 v[94:97], v[242:245], v[210:213], v[94:97]
	v_mfma_f32_16x16x32_bf16 v[86:89], v[234:237], v[218:221], v[86:89]
	v_mfma_f32_16x16x32_bf16 v[78:81], v[242:245], v[218:221], v[78:81]
	v_mfma_f32_16x16x32_bf16 v[70:73], v[234:237], v[226:229], v[70:73]
	v_mfma_f32_16x16x32_bf16 v[66:69], v[242:245], v[226:229], v[66:69]
	s_barrier
	s_mov_b32 m0, s47
	v_lshl_add_u64 v[248:249], s[48:49], 0, v[162:163]
	ds_read_b128 v[172:175], v180 offset:16384
	ds_read_b128 v[182:185], v180 offset:17408
	ds_read_b128 v[206:209], v180 offset:18432
	ds_read_b128 v[210:213], v180 offset:19456
	ds_read_b128 v[214:217], v180 offset:20480
	ds_read_b128 v[218:221], v180 offset:21504
	ds_read_b128 v[222:225], v180 offset:22528
	ds_read_b128 v[226:229], v180 offset:23552
	global_load_lds_dwordx4 v[248:249], off
	s_mov_b32 m0, s50
	v_lshl_add_u64 v[250:251], s[48:49], 0, v[164:165]
	global_load_lds_dwordx4 v[250:251], off
	s_barrier
	s_waitcnt lgkmcnt(0)
	v_mfma_f32_16x16x32_bf16 v[62:65], v[130:133], v[172:175], v[62:65]
	v_mfma_f32_16x16x32_bf16 v[58:61], v[138:141], v[172:175], v[58:61]
	v_mfma_f32_16x16x32_bf16 v[50:53], v[130:133], v[206:209], v[50:53]
	v_mfma_f32_16x16x32_bf16 v[42:45], v[138:141], v[206:209], v[42:45]
	v_mfma_f32_16x16x32_bf16 v[34:37], v[130:133], v[214:217], v[34:37]
	v_mfma_f32_16x16x32_bf16 v[26:29], v[138:141], v[214:217], v[26:29]
	v_mfma_f32_16x16x32_bf16 v[18:21], v[130:133], v[222:225], v[18:21]
	v_mfma_f32_16x16x32_bf16 v[10:13], v[138:141], v[222:225], v[10:13]
	v_mfma_f32_16x16x32_bf16 v[62:65], v[134:137], v[182:185], v[62:65]
	v_mfma_f32_16x16x32_bf16 v[58:61], v[142:145], v[182:185], v[58:61]
	v_mfma_f32_16x16x32_bf16 v[50:53], v[134:137], v[210:213], v[50:53]
	v_mfma_f32_16x16x32_bf16 v[42:45], v[142:145], v[210:213], v[42:45]
	v_mfma_f32_16x16x32_bf16 v[34:37], v[134:137], v[218:221], v[34:37]
	v_mfma_f32_16x16x32_bf16 v[26:29], v[142:145], v[218:221], v[26:29]
	v_mfma_f32_16x16x32_bf16 v[18:21], v[134:137], v[226:229], v[18:21]
	v_mfma_f32_16x16x32_bf16 v[10:13], v[142:145], v[226:229], v[10:13]
	s_barrier
	s_add_u32 s66, s22, 0x40000
	s_addc_u32 s67, s23, 0
	s_add_i32 s65, s68, s27
	s_mov_b32 m0, s65
	s_nop 0
	global_load_lds_dwordx4 v0, s[66:67]
	s_add_i32 m0, s65, 0x2000
	v_lshl_add_u64 v[130:131], s[66:67], 0, v[166:167]
	global_load_lds_dwordx4 v[130:131], off
	s_waitcnt vmcnt(6)
	s_barrier
	v_mfma_f32_16x16x32_bf16 v[54:57], v[230:233], v[172:175], v[54:57]
	v_mfma_f32_16x16x32_bf16 v[46:49], v[238:241], v[172:175], v[46:49]
	v_mfma_f32_16x16x32_bf16 v[38:41], v[230:233], v[206:209], v[38:41]
	v_mfma_f32_16x16x32_bf16 v[30:33], v[238:241], v[206:209], v[30:33]
	v_mfma_f32_16x16x32_bf16 v[22:25], v[230:233], v[214:217], v[22:25]
	v_mfma_f32_16x16x32_bf16 v[14:17], v[238:241], v[214:217], v[14:17]
	v_mfma_f32_16x16x32_bf16 v[6:9], v[230:233], v[222:225], v[6:9]
	v_mfma_f32_16x16x32_bf16 v[2:5], v[238:241], v[222:225], v[2:5]
	v_mfma_f32_16x16x32_bf16 v[54:57], v[234:237], v[182:185], v[54:57]
	v_mfma_f32_16x16x32_bf16 v[46:49], v[242:245], v[182:185], v[46:49]
	v_mfma_f32_16x16x32_bf16 v[38:41], v[234:237], v[210:213], v[38:41]
	v_mfma_f32_16x16x32_bf16 v[30:33], v[242:245], v[210:213], v[30:33]
	v_mfma_f32_16x16x32_bf16 v[22:25], v[234:237], v[218:221], v[22:25]
	v_mfma_f32_16x16x32_bf16 v[14:17], v[242:245], v[218:221], v[14:17]
	v_mfma_f32_16x16x32_bf16 v[6:9], v[234:237], v[226:229], v[6:9]
	v_mfma_f32_16x16x32_bf16 v[2:5], v[242:245], v[226:229], v[2:5]
	s_barrier
	s_add_i32 s65, 0, 0x18000
	v_add_u32_e32 v142, s65, v178
	ds_read_b128 v[130:133], v142
	ds_read_b128 v[134:137], v142 offset:1024
	ds_read_b128 v[138:141], v142 offset:2048
	ds_read_b128 v[142:145], v142 offset:3072
	s_add_u32 s48, s48, 0x40000
	s_addc_u32 s49, s49, 0
	s_mov_b32 m0, s51
	v_lshl_add_u64 v[230:231], s[48:49], 0, v[162:163]
	ds_read_b128 v[172:175], v180 offset:32768
	ds_read_b128 v[182:185], v180 offset:33792
	ds_read_b128 v[206:209], v180 offset:34816
	ds_read_b128 v[210:213], v180 offset:35840
	ds_read_b128 v[214:217], v180 offset:36864
	ds_read_b128 v[218:221], v180 offset:37888
	ds_read_b128 v[222:225], v180 offset:38912
	ds_read_b128 v[226:229], v180 offset:39936
	global_load_lds_dwordx4 v[230:231], off
	s_mov_b32 m0, s54
	v_lshl_add_u64 v[230:231], s[48:49], 0, v[164:165]
	global_load_lds_dwordx4 v[230:231], off
	s_waitcnt lgkmcnt(8)
	s_barrier
	s_waitcnt lgkmcnt(0)
	v_mfma_f32_16x16x32_bf16 v[126:129], v[130:133], v[172:175], v[126:129]
	v_mfma_f32_16x16x32_bf16 v[122:125], v[138:141], v[172:175], v[122:125]
	v_mfma_f32_16x16x32_bf16 v[114:117], v[130:133], v[206:209], v[114:117]
	v_mfma_f32_16x16x32_bf16 v[106:109], v[138:141], v[206:209], v[106:109]
	v_mfma_f32_16x16x32_bf16 v[98:101], v[130:133], v[214:217], v[98:101]
	v_mfma_f32_16x16x32_bf16 v[90:93], v[138:141], v[214:217], v[90:93]
	v_mfma_f32_16x16x32_bf16 v[82:85], v[130:133], v[222:225], v[82:85]
	v_mfma_f32_16x16x32_bf16 v[74:77], v[138:141], v[222:225], v[74:77]
	v_mfma_f32_16x16x32_bf16 v[126:129], v[134:137], v[182:185], v[126:129]
	v_mfma_f32_16x16x32_bf16 v[122:125], v[142:145], v[182:185], v[122:125]
	v_mfma_f32_16x16x32_bf16 v[114:117], v[134:137], v[210:213], v[114:117]
	v_mfma_f32_16x16x32_bf16 v[106:109], v[142:145], v[210:213], v[106:109]
	v_mfma_f32_16x16x32_bf16 v[98:101], v[134:137], v[218:221], v[98:101]
	v_mfma_f32_16x16x32_bf16 v[90:93], v[142:145], v[218:221], v[90:93]
	v_mfma_f32_16x16x32_bf16 v[82:85], v[134:137], v[226:229], v[82:85]
	v_mfma_f32_16x16x32_bf16 v[74:77], v[142:145], v[226:229], v[74:77]
	s_barrier
	s_add_i32 s48, 0, 0x1c000
	s_add_i32 s49, s65, s27
	v_add_u32_e32 v181, s48, v178
	v_lshl_add_u64 v[186:187], v[186:187], 0, s[94:95]
	s_mov_b32 m0, s49
	ds_read_b128 v[230:233], v181
	ds_read_b128 v[234:237], v181 offset:1024
	ds_read_b128 v[238:241], v181 offset:2048
	ds_read_b128 v[242:245], v181 offset:3072
	global_load_lds_dwordx4 v[186:187], off
	s_add_i32 m0, s49, 0x2000
	v_lshl_add_u64 v[186:187], v[246:247], 0, s[94:95]
	global_load_lds_dwordx4 v[186:187], off
	s_barrier
	s_waitcnt lgkmcnt(0)
	v_mfma_f32_16x16x32_bf16 v[118:121], v[230:233], v[172:175], v[118:121]
	v_mfma_f32_16x16x32_bf16 v[110:113], v[238:241], v[172:175], v[110:113]
	v_mfma_f32_16x16x32_bf16 v[102:105], v[230:233], v[206:209], v[102:105]
	v_mfma_f32_16x16x32_bf16 v[94:97], v[238:241], v[206:209], v[94:97]
	v_mfma_f32_16x16x32_bf16 v[86:89], v[230:233], v[214:217], v[86:89]
	v_mfma_f32_16x16x32_bf16 v[78:81], v[238:241], v[214:217], v[78:81]
	v_mfma_f32_16x16x32_bf16 v[70:73], v[230:233], v[222:225], v[70:73]
	v_mfma_f32_16x16x32_bf16 v[66:69], v[238:241], v[222:225], v[66:69]
	v_mfma_f32_16x16x32_bf16 v[118:121], v[234:237], v[182:185], v[118:121]
	v_mfma_f32_16x16x32_bf16 v[110:113], v[242:245], v[182:185], v[110:113]
	v_mfma_f32_16x16x32_bf16 v[102:105], v[234:237], v[210:213], v[102:105]
	v_mfma_f32_16x16x32_bf16 v[94:97], v[242:245], v[210:213], v[94:97]
	v_mfma_f32_16x16x32_bf16 v[86:89], v[234:237], v[218:221], v[86:89]
	v_mfma_f32_16x16x32_bf16 v[78:81], v[242:245], v[218:221], v[78:81]
	v_mfma_f32_16x16x32_bf16 v[70:73], v[234:237], v[226:229], v[70:73]
	v_mfma_f32_16x16x32_bf16 v[66:69], v[242:245], v[226:229], v[66:69]
	s_barrier
	s_mov_b32 m0, s55
	v_lshl_add_u64 v[186:187], v[248:249], 0, s[94:95]
	ds_read_b128 v[172:175], v180 offset:49152
	ds_read_b128 v[182:185], v180 offset:50176
	ds_read_b128 v[206:209], v180 offset:51200
	ds_read_b128 v[210:213], v180 offset:52224
	ds_read_b128 v[214:217], v180 offset:53248
	ds_read_b128 v[218:221], v180 offset:54272
	ds_read_b128 v[222:225], v180 offset:55296
	ds_read_b128 v[226:229], v180 offset:56320
	global_load_lds_dwordx4 v[186:187], off
	s_mov_b32 m0, s56
	v_lshl_add_u64 v[186:187], v[250:251], 0, s[94:95]
	global_load_lds_dwordx4 v[186:187], off
	s_barrier
	s_waitcnt lgkmcnt(0)
	v_mfma_f32_16x16x32_bf16 v[62:65], v[130:133], v[172:175], v[62:65]
	v_mfma_f32_16x16x32_bf16 v[58:61], v[138:141], v[172:175], v[58:61]
	v_mfma_f32_16x16x32_bf16 v[50:53], v[130:133], v[206:209], v[50:53]
	v_mfma_f32_16x16x32_bf16 v[42:45], v[138:141], v[206:209], v[42:45]
	v_mfma_f32_16x16x32_bf16 v[34:37], v[130:133], v[214:217], v[34:37]
	v_mfma_f32_16x16x32_bf16 v[26:29], v[138:141], v[214:217], v[26:29]
	v_mfma_f32_16x16x32_bf16 v[18:21], v[130:133], v[222:225], v[18:21]
	v_mfma_f32_16x16x32_bf16 v[10:13], v[138:141], v[222:225], v[10:13]
	v_mfma_f32_16x16x32_bf16 v[62:65], v[134:137], v[182:185], v[62:65]
	v_mfma_f32_16x16x32_bf16 v[58:61], v[142:145], v[182:185], v[58:61]
	v_mfma_f32_16x16x32_bf16 v[50:53], v[134:137], v[210:213], v[50:53]
	v_mfma_f32_16x16x32_bf16 v[42:45], v[142:145], v[210:213], v[42:45]
	v_mfma_f32_16x16x32_bf16 v[34:37], v[134:137], v[218:221], v[34:37]
	v_mfma_f32_16x16x32_bf16 v[26:29], v[142:145], v[218:221], v[26:29]
	v_mfma_f32_16x16x32_bf16 v[18:21], v[134:137], v[226:229], v[18:21]
	v_mfma_f32_16x16x32_bf16 v[10:13], v[142:145], v[226:229], v[10:13]
	s_barrier
	s_add_u32 s22, s22, 0x40080
	s_addc_u32 s23, s23, 0
	s_add_i32 s48, s48, s27
	s_mov_b32 m0, s48
	s_nop 0
	global_load_lds_dwordx4 v0, s[22:23]
	s_add_i32 m0, s48, 0x2000
	v_lshl_add_u64 v[130:131], s[22:23], 0, v[166:167]
	global_load_lds_dwordx4 v[130:131], off
	s_waitcnt vmcnt(6)
	s_barrier
	v_mfma_f32_16x16x32_bf16 v[54:57], v[230:233], v[172:175], v[54:57]
	v_mfma_f32_16x16x32_bf16 v[46:49], v[238:241], v[172:175], v[46:49]
	v_mfma_f32_16x16x32_bf16 v[38:41], v[230:233], v[206:209], v[38:41]
	v_mfma_f32_16x16x32_bf16 v[30:33], v[238:241], v[206:209], v[30:33]
	v_mfma_f32_16x16x32_bf16 v[22:25], v[230:233], v[214:217], v[22:25]
	v_mfma_f32_16x16x32_bf16 v[14:17], v[238:241], v[214:217], v[14:17]
	v_mfma_f32_16x16x32_bf16 v[6:9], v[230:233], v[222:225], v[6:9]
	v_mfma_f32_16x16x32_bf16 v[2:5], v[238:241], v[222:225], v[2:5]
	v_mfma_f32_16x16x32_bf16 v[54:57], v[234:237], v[182:185], v[54:57]
	v_mfma_f32_16x16x32_bf16 v[46:49], v[242:245], v[182:185], v[46:49]
	v_mfma_f32_16x16x32_bf16 v[38:41], v[234:237], v[210:213], v[38:41]
	v_mfma_f32_16x16x32_bf16 v[30:33], v[242:245], v[210:213], v[30:33]
	v_mfma_f32_16x16x32_bf16 v[22:25], v[234:237], v[218:221], v[22:25]
	v_mfma_f32_16x16x32_bf16 v[14:17], v[242:245], v[218:221], v[14:17]
	v_mfma_f32_16x16x32_bf16 v[6:9], v[234:237], v[226:229], v[6:9]
	v_mfma_f32_16x16x32_bf16 v[2:5], v[242:245], v[226:229], v[2:5]
	s_barrier
	s_add_i32 s64, s64, 2
	s_add_u32 s0, s0, 0x100
	s_addc_u32 s1, s1, 0
	s_add_u32 s62, s62, 0x100
	s_addc_u32 s63, s63, 0
	s_cmp_gt_u32 s64, 13
	s_cbranch_scc0 .LBB0_57
	v_lshl_or_b32 v172, s59, 8, v179
	v_ashrrev_i32_e32 v173, 31, v172
	v_cndmask_b32_e64 v131, 0, 1, s[2:3]
	v_lshl_add_u64 v[174:175], v[172:173], 2, s[8:9]
	v_mov_b32_e32 v130, 0
	v_cmp_ne_u32_e64 s[0:1], 1, v131
	s_andn2_b64 vcc, exec, s[2:3]
	v_mov_b32_e32 v134, 0
	v_mov_b32_e32 v135, 0
	v_mov_b32_e32 v136, 0
	v_mov_b32_e32 v137, 0
	s_cbranch_vccnz .LBB0_60
	global_load_dwordx4 v[134:137], v[174:175], off

.Lkprio_4:
.LBB0_95:
	s_add_u32 s22, s8, 0xfffc0080
	s_addc_u32 s23, s9, -1
	s_add_i32 s63, 0, 0x10000
	v_add_u32_e32 v78, s63, v178
	ds_read_b128 v[58:61], v78
	ds_read_b128 v[66:69], v78 offset:1024
	ds_read_b128 v[74:77], v78 offset:2048
	ds_read_b128 v[78:81], v78 offset:3072
	s_cmp_eq_u32 s49, 12
	s_cselect_b32 s29, s25, s23
	s_cselect_b32 s28, s26, s22
	s_cselect_b32 s23, s27, s47
	s_cselect_b32 s22, s30, s31
	v_lshl_add_u64 v[186:187], s[8:9], 0, v[168:169]
	s_add_i32 m0, s3, 0xc000
	ds_read_b128 v[172:175], v180
	ds_read_b128 v[182:185], v180 offset:1024
	ds_read_b128 v[206:209], v180 offset:2048
	ds_read_b128 v[210:213], v180 offset:3072
	ds_read_b128 v[214:217], v180 offset:4096
	ds_read_b128 v[218:221], v180 offset:5120
	ds_read_b128 v[222:225], v180 offset:6144
	ds_read_b128 v[226:229], v180 offset:7168
	global_load_lds_dwordx4 v[186:187], off
	s_add_i32 m0, s3, 0xe000
	s_nop 0
	global_load_lds_dwordx4 v170, s[8:9]
	s_waitcnt lgkmcnt(8)
	s_barrier
	s_waitcnt lgkmcnt(0)
	v_mfma_f32_16x16x32_bf16 v[142:145], v[58:61], v[172:175], v[142:145]
	v_mfma_f32_16x16x32_bf16 v[138:141], v[74:77], v[172:175], v[138:141]
	v_mfma_f32_16x16x32_bf16 v[126:129], v[58:61], v[206:209], v[126:129]
	v_mfma_f32_16x16x32_bf16 v[118:121], v[74:77], v[206:209], v[118:121]
	v_mfma_f32_16x16x32_bf16 v[110:113], v[58:61], v[214:217], v[110:113]
	v_mfma_f32_16x16x32_bf16 v[102:105], v[74:77], v[214:217], v[102:105]
	v_mfma_f32_16x16x32_bf16 v[94:97], v[58:61], v[222:225], v[94:97]
	v_mfma_f32_16x16x32_bf16 v[86:89], v[74:77], v[222:225], v[86:89]
	v_mfma_f32_16x16x32_bf16 v[142:145], v[66:69], v[182:185], v[142:145]
	v_mfma_f32_16x16x32_bf16 v[138:141], v[78:81], v[182:185], v[138:141]
	v_mfma_f32_16x16x32_bf16 v[126:129], v[66:69], v[210:213], v[126:129]
	v_mfma_f32_16x16x32_bf16 v[118:121], v[78:81], v[210:213], v[118:121]
	v_mfma_f32_16x16x32_bf16 v[110:113], v[66:69], v[218:221], v[110:113]
	v_mfma_f32_16x16x32_bf16 v[102:105], v[78:81], v[218:221], v[102:105]
	v_mfma_f32_16x16x32_bf16 v[94:97], v[66:69], v[226:229], v[94:97]
	v_mfma_f32_16x16x32_bf16 v[86:89], v[78:81], v[226:229], v[86:89]
	s_barrier
	s_add_i32 s66, 0, 0x14000
	s_add_i32 s63, s63, s37
	v_add_u32_e32 v181, s66, v178
	v_lshl_add_u64 v[186:187], s[22:23], 0, v[0:1]
	s_mov_b32 m0, s63
	ds_read_b128 v[230:233], v181
	ds_read_b128 v[234:237], v181 offset:1024
	ds_read_b128 v[238:241], v181 offset:2048
	ds_read_b128 v[242:245], v181 offset:3072
	global_load_lds_dwordx4 v[186:187], off
	s_add_i32 m0, s63, 0x2000
	v_lshl_add_u64 v[246:247], s[22:23], 0, v[166:167]
	global_load_lds_dwordx4 v[246:247], off
	s_barrier
	s_waitcnt lgkmcnt(0)
	v_mfma_f32_16x16x32_bf16 v[134:137], v[230:233], v[172:175], v[134:137]
	v_mfma_f32_16x16x32_bf16 v[130:133], v[238:241], v[172:175], v[130:133]
	v_mfma_f32_16x16x32_bf16 v[122:125], v[230:233], v[206:209], v[122:125]
	v_mfma_f32_16x16x32_bf16 v[114:117], v[238:241], v[206:209], v[114:117]
	v_mfma_f32_16x16x32_bf16 v[106:109], v[230:233], v[214:217], v[106:109]
	v_mfma_f32_16x16x32_bf16 v[98:101], v[238:241], v[214:217], v[98:101]
	v_mfma_f32_16x16x32_bf16 v[90:93], v[230:233], v[222:225], v[90:93]
	v_mfma_f32_16x16x32_bf16 v[82:85], v[238:241], v[222:225], v[82:85]
	v_mfma_f32_16x16x32_bf16 v[134:137], v[234:237], v[182:185], v[134:137]
	v_mfma_f32_16x16x32_bf16 v[130:133], v[242:245], v[182:185], v[130:133]
	v_mfma_f32_16x16x32_bf16 v[122:125], v[234:237], v[210:213], v[122:125]
	v_mfma_f32_16x16x32_bf16 v[114:117], v[242:245], v[210:213], v[114:117]
	v_mfma_f32_16x16x32_bf16 v[106:109], v[234:237], v[218:221], v[106:109]
	v_mfma_f32_16x16x32_bf16 v[98:101], v[242:245], v[218:221], v[98:101]
	v_mfma_f32_16x16x32_bf16 v[90:93], v[234:237], v[226:229], v[90:93]
	v_mfma_f32_16x16x32_bf16 v[82:85], v[242:245], v[226:229], v[82:85]
	s_barrier
	s_mov_b32 m0, s3
	v_lshl_add_u64 v[248:249], s[28:29], 0, v[162:163]
	ds_read_b128 v[172:175], v180 offset:16384
	ds_read_b128 v[182:185], v180 offset:17408
	ds_read_b128 v[206:209], v180 offset:18432
	ds_read_b128 v[210:213], v180 offset:19456
	ds_read_b128 v[214:217], v180 offset:20480
	ds_read_b128 v[218:221], v180 offset:21504
	ds_read_b128 v[222:225], v180 offset:22528
	ds_read_b128 v[226:229], v180 offset:23552
	global_load_lds_dwordx4 v[248:249], off
	s_mov_b32 m0, s56
	v_lshl_add_u64 v[250:251], s[28:29], 0, v[164:165]
	global_load_lds_dwordx4 v[250:251], off
	s_barrier
	s_waitcnt lgkmcnt(0)
	v_mfma_f32_16x16x32_bf16 v[70:73], v[58:61], v[172:175], v[70:73]
	v_mfma_f32_16x16x32_bf16 v[54:57], v[74:77], v[172:175], v[54:57]
	v_mfma_f32_16x16x32_bf16 v[46:49], v[58:61], v[206:209], v[46:49]
	v_mfma_f32_16x16x32_bf16 v[38:41], v[74:77], v[206:209], v[38:41]
	v_mfma_f32_16x16x32_bf16 v[30:33], v[58:61], v[214:217], v[30:33]
	v_mfma_f32_16x16x32_bf16 v[22:25], v[74:77], v[214:217], v[22:25]
	v_mfma_f32_16x16x32_bf16 v[14:17], v[58:61], v[222:225], v[14:17]
	v_mfma_f32_16x16x32_bf16 v[6:9], v[74:77], v[222:225], v[6:9]
	v_mfma_f32_16x16x32_bf16 v[70:73], v[66:69], v[182:185], v[70:73]
	v_mfma_f32_16x16x32_bf16 v[54:57], v[78:81], v[182:185], v[54:57]
	v_mfma_f32_16x16x32_bf16 v[46:49], v[66:69], v[210:213], v[46:49]
	v_mfma_f32_16x16x32_bf16 v[38:41], v[78:81], v[210:213], v[38:41]
	v_mfma_f32_16x16x32_bf16 v[30:33], v[66:69], v[218:221], v[30:33]
	v_mfma_f32_16x16x32_bf16 v[22:25], v[78:81], v[218:221], v[22:25]
	v_mfma_f32_16x16x32_bf16 v[14:17], v[66:69], v[226:229], v[14:17]
	v_mfma_f32_16x16x32_bf16 v[6:9], v[78:81], v[226:229], v[6:9]
	s_barrier
	s_add_u32 s64, s22, 0x40000
	s_addc_u32 s65, s23, 0
	s_add_i32 s63, s66, s37
	s_mov_b32 m0, s63
	s_nop 0
	global_load_lds_dwordx4 v0, s[64:65]
	s_add_i32 m0, s63, 0x2000
	s_nop 0
	global_load_lds_dwordx4 v166, s[64:65]
	s_waitcnt vmcnt(6)
	s_barrier
	v_mfma_f32_16x16x32_bf16 v[50:53], v[238:241], v[172:175], v[50:53]
	v_mfma_f32_16x16x32_bf16 v[42:45], v[230:233], v[206:209], v[42:45]
	v_mfma_f32_16x16x32_bf16 v[34:37], v[238:241], v[206:209], v[34:37]
	v_mfma_f32_16x16x32_bf16 v[26:29], v[230:233], v[214:217], v[26:29]
	v_mfma_f32_16x16x32_bf16 v[18:21], v[238:241], v[214:217], v[18:21]
	v_mfma_f32_16x16x32_bf16 v[10:13], v[230:233], v[222:225], v[10:13]
	v_mfma_f32_16x16x32_bf16 v[2:5], v[238:241], v[222:225], v[2:5]
	v_mfma_f32_16x16x32_bf16 v[58:61], v[230:233], v[172:175], v[62:65]
	v_mfma_f32_16x16x32_bf16 v[50:53], v[242:245], v[182:185], v[50:53]
	v_mfma_f32_16x16x32_bf16 v[42:45], v[234:237], v[210:213], v[42:45]
	v_mfma_f32_16x16x32_bf16 v[34:37], v[242:245], v[210:213], v[34:37]
	v_mfma_f32_16x16x32_bf16 v[26:29], v[234:237], v[218:221], v[26:29]
	v_mfma_f32_16x16x32_bf16 v[18:21], v[242:245], v[218:221], v[18:21]
	v_mfma_f32_16x16x32_bf16 v[10:13], v[234:237], v[226:229], v[10:13]
	v_mfma_f32_16x16x32_bf16 v[2:5], v[242:245], v[226:229], v[2:5]
	v_mfma_f32_16x16x32_bf16 v[58:61], v[234:237], v[182:185], v[58:61]
	s_barrier
	s_add_i32 s63, 0, 0x18000
	v_add_u32_e32 v78, s63, v178
	ds_read_b128 v[62:65], v78
	ds_read_b128 v[66:69], v78 offset:1024
	ds_read_b128 v[74:77], v78 offset:2048
	ds_read_b128 v[78:81], v78 offset:3072
	s_add_u32 s28, s28, 0x40000
	s_addc_u32 s29, s29, 0
	s_mov_b32 m0, s57
	v_lshl_add_u64 v[230:231], s[28:29], 0, v[162:163]
	ds_read_b128 v[172:175], v180 offset:32768
	ds_read_b128 v[182:185], v180 offset:33792
	ds_read_b128 v[206:209], v180 offset:34816
	ds_read_b128 v[210:213], v180 offset:35840
	ds_read_b128 v[214:217], v180 offset:36864
	ds_read_b128 v[218:221], v180 offset:37888
	ds_read_b128 v[222:225], v180 offset:38912
	ds_read_b128 v[226:229], v180 offset:39936
	global_load_lds_dwordx4 v[230:231], off
	s_mov_b32 m0, s58
	s_nop 0
	global_load_lds_dwordx4 v164, s[28:29]
	s_waitcnt lgkmcnt(8)
	s_barrier
	s_waitcnt lgkmcnt(0)
	v_mfma_f32_16x16x32_bf16 v[142:145], v[62:65], v[172:175], v[142:145]
	v_mfma_f32_16x16x32_bf16 v[138:141], v[74:77], v[172:175], v[138:141]
	v_mfma_f32_16x16x32_bf16 v[126:129], v[62:65], v[206:209], v[126:129]
	v_mfma_f32_16x16x32_bf16 v[118:121], v[74:77], v[206:209], v[118:121]
	v_mfma_f32_16x16x32_bf16 v[110:113], v[62:65], v[214:217], v[110:113]
	v_mfma_f32_16x16x32_bf16 v[102:105], v[74:77], v[214:217], v[102:105]
	v_mfma_f32_16x16x32_bf16 v[94:97], v[62:65], v[222:225], v[94:97]
	v_mfma_f32_16x16x32_bf16 v[86:89], v[74:77], v[222:225], v[86:89]
	v_mfma_f32_16x16x32_bf16 v[142:145], v[66:69], v[182:185], v[142:145]
	v_mfma_f32_16x16x32_bf16 v[138:141], v[78:81], v[182:185], v[138:141]
	v_mfma_f32_16x16x32_bf16 v[126:129], v[66:69], v[210:213], v[126:129]
	v_mfma_f32_16x16x32_bf16 v[118:121], v[78:81], v[210:213], v[118:121]
	v_mfma_f32_16x16x32_bf16 v[110:113], v[66:69], v[218:221], v[110:113]
	v_mfma_f32_16x16x32_bf16 v[102:105], v[78:81], v[218:221], v[102:105]
	v_mfma_f32_16x16x32_bf16 v[94:97], v[66:69], v[226:229], v[94:97]
	v_mfma_f32_16x16x32_bf16 v[86:89], v[78:81], v[226:229], v[86:89]
	s_barrier
	s_add_i32 s28, 0, 0x1c000
	s_add_i32 s29, s63, s37
	v_add_u32_e32 v181, s28, v178
	v_lshl_add_u64 v[186:187], v[186:187], 0, s[94:95]
	s_mov_b32 m0, s29
	ds_read_b128 v[230:233], v181
	ds_read_b128 v[234:237], v181 offset:1024
	ds_read_b128 v[238:241], v181 offset:2048
	ds_read_b128 v[242:245], v181 offset:3072
	global_load_lds_dwordx4 v[186:187], off
	s_add_i32 m0, s29, 0x2000
	v_lshl_add_u64 v[186:187], v[246:247], 0, s[94:95]
	global_load_lds_dwordx4 v[186:187], off
	s_barrier
	s_waitcnt lgkmcnt(0)
	v_mfma_f32_16x16x32_bf16 v[134:137], v[230:233], v[172:175], v[134:137]
	v_mfma_f32_16x16x32_bf16 v[130:133], v[238:241], v[172:175], v[130:133]
	v_mfma_f32_16x16x32_bf16 v[122:125], v[230:233], v[206:209], v[122:125]
	v_mfma_f32_16x16x32_bf16 v[114:117], v[238:241], v[206:209], v[114:117]
	v_mfma_f32_16x16x32_bf16 v[106:109], v[230:233], v[214:217], v[106:109]
	v_mfma_f32_16x16x32_bf16 v[98:101], v[238:241], v[214:217], v[98:101]
	v_mfma_f32_16x16x32_bf16 v[90:93], v[230:233], v[222:225], v[90:93]
	v_mfma_f32_16x16x32_bf16 v[82:85], v[238:241], v[222:225], v[82:85]
	v_mfma_f32_16x16x32_bf16 v[134:137], v[234:237], v[182:185], v[134:137]
	v_mfma_f32_16x16x32_bf16 v[130:133], v[242:245], v[182:185], v[130:133]
	v_mfma_f32_16x16x32_bf16 v[122:125], v[234:237], v[210:213], v[122:125]
	v_mfma_f32_16x16x32_bf16 v[114:117], v[242:245], v[210:213], v[114:117]
	v_mfma_f32_16x16x32_bf16 v[106:109], v[234:237], v[218:221], v[106:109]
	v_mfma_f32_16x16x32_bf16 v[98:101], v[242:245], v[218:221], v[98:101]
	v_mfma_f32_16x16x32_bf16 v[90:93], v[234:237], v[226:229], v[90:93]
	v_mfma_f32_16x16x32_bf16 v[82:85], v[242:245], v[226:229], v[82:85]
	s_barrier
	s_mov_b32 m0, s59
	v_lshl_add_u64 v[186:187], v[248:249], 0, s[94:95]
	ds_read_b128 v[172:175], v180 offset:49152
	ds_read_b128 v[182:185], v180 offset:50176
	ds_read_b128 v[206:209], v180 offset:51200
	ds_read_b128 v[210:213], v180 offset:52224
	ds_read_b128 v[214:217], v180 offset:53248
	ds_read_b128 v[218:221], v180 offset:54272
	ds_read_b128 v[222:225], v180 offset:55296
	ds_read_b128 v[226:229], v180 offset:56320
	global_load_lds_dwordx4 v[186:187], off
	s_mov_b32 m0, s60
	v_lshl_add_u64 v[186:187], v[250:251], 0, s[94:95]
	global_load_lds_dwordx4 v[186:187], off
	s_barrier
	s_waitcnt lgkmcnt(0)
	v_mfma_f32_16x16x32_bf16 v[70:73], v[62:65], v[172:175], v[70:73]
	v_mfma_f32_16x16x32_bf16 v[54:57], v[74:77], v[172:175], v[54:57]
	v_mfma_f32_16x16x32_bf16 v[46:49], v[62:65], v[206:209], v[46:49]
	v_mfma_f32_16x16x32_bf16 v[38:41], v[74:77], v[206:209], v[38:41]
	v_mfma_f32_16x16x32_bf16 v[30:33], v[62:65], v[214:217], v[30:33]
	v_mfma_f32_16x16x32_bf16 v[22:25], v[74:77], v[214:217], v[22:25]
	v_mfma_f32_16x16x32_bf16 v[14:17], v[62:65], v[222:225], v[14:17]
	v_mfma_f32_16x16x32_bf16 v[6:9], v[74:77], v[222:225], v[6:9]
	v_mfma_f32_16x16x32_bf16 v[70:73], v[66:69], v[182:185], v[70:73]
	v_mfma_f32_16x16x32_bf16 v[54:57], v[78:81], v[182:185], v[54:57]
	v_mfma_f32_16x16x32_bf16 v[46:49], v[66:69], v[210:213], v[46:49]
	v_mfma_f32_16x16x32_bf16 v[38:41], v[78:81], v[210:213], v[38:41]
	v_mfma_f32_16x16x32_bf16 v[30:33], v[66:69], v[218:221], v[30:33]
	v_mfma_f32_16x16x32_bf16 v[22:25], v[78:81], v[218:221], v[22:25]
	v_mfma_f32_16x16x32_bf16 v[14:17], v[66:69], v[226:229], v[14:17]
	v_mfma_f32_16x16x32_bf16 v[6:9], v[78:81], v[226:229], v[6:9]
	s_barrier
	s_add_u32 s22, s22, 0x40080
	s_addc_u32 s23, s23, 0
	s_add_i32 s28, s28, s37
	s_mov_b32 m0, s28
	s_nop 0
	global_load_lds_dwordx4 v0, s[22:23]
	s_add_i32 m0, s28, 0x2000
	s_nop 0
	global_load_lds_dwordx4 v166, s[22:23]
	s_waitcnt vmcnt(6)
	s_barrier
	v_mfma_f32_16x16x32_bf16 v[58:61], v[230:233], v[172:175], v[58:61]
	v_mfma_f32_16x16x32_bf16 v[50:53], v[238:241], v[172:175], v[50:53]
	v_mfma_f32_16x16x32_bf16 v[42:45], v[230:233], v[206:209], v[42:45]
	v_mfma_f32_16x16x32_bf16 v[34:37], v[238:241], v[206:209], v[34:37]
	v_mfma_f32_16x16x32_bf16 v[26:29], v[230:233], v[214:217], v[26:29]
	v_mfma_f32_16x16x32_bf16 v[18:21], v[238:241], v[214:217], v[18:21]
	v_mfma_f32_16x16x32_bf16 v[10:13], v[230:233], v[222:225], v[10:13]
	v_mfma_f32_16x16x32_bf16 v[2:5], v[238:241], v[222:225], v[2:5]
	v_mfma_f32_16x16x32_bf16 v[62:65], v[234:237], v[182:185], v[58:61]
	v_mfma_f32_16x16x32_bf16 v[50:53], v[242:245], v[182:185], v[50:53]
	v_mfma_f32_16x16x32_bf16 v[42:45], v[234:237], v[210:213], v[42:45]
	v_mfma_f32_16x16x32_bf16 v[34:37], v[242:245], v[210:213], v[34:37]
	v_mfma_f32_16x16x32_bf16 v[26:29], v[234:237], v[218:221], v[26:29]
	v_mfma_f32_16x16x32_bf16 v[18:21], v[242:245], v[218:221], v[18:21]
	v_mfma_f32_16x16x32_bf16 v[10:13], v[234:237], v[226:229], v[10:13]
	v_mfma_f32_16x16x32_bf16 v[2:5], v[242:245], v[226:229], v[2:5]
	s_barrier
	s_add_i32 s49, s49, 2
	s_add_u32 s8, s8, 0x100
	s_addc_u32 s9, s9, 0
	s_add_u32 s31, s31, 0x100
	s_addc_u32 s47, s47, 0
	s_cmp_gt_u32 s49, 13
	s_cbranch_scc0 .LBB0_95
	v_lshl_or_b32 v172, s24, 7, v179
	v_ashrrev_i32_e32 v173, 31, v172
	v_lshlrev_b64 v[58:59], 2, v[172:173]
	v_lshl_add_u64 v[60:61], s[40:41], 0, v[58:59]
	v_lshl_add_u64 v[74:75], s[44:45], 0, v[58:59]
	global_load_dwordx4 v[66:69], v[60:61], off offset:16
	global_load_dwordx4 v[78:81], v[60:61], off
	s_nop 0
	global_load_dwordx4 v[58:61], v[74:75], off offset:16
	s_nop 0
	global_load_dwordx4 v[74:77], v[74:75], off
	v_lshl_add_u32 v174, s2, 8, v177
	v_ashrrev_i32_e32 v175, 31, v174
	v_lshl_add_u64 v[172:173], v[172:173], 1, s[20:21]
	v_lshlrev_b64 v[182:183], 11, v[174:175]
	s_mov_b32 s2, 0x50000
	s_mov_b32 s24, s46
	s_mov_b64 s[22:23], s[54:55]
	s_mov_b64 s[8:9], s[50:51]
	s_waitcnt vmcnt(0)
	v_add_f32_e32 v138, v138, v66
	v_add_f32_e32 v126, v126, v78
	v_add_f32_e32 v130, v130, v58
	v_mul_f32_e32 v130, 0xbfb8aa3b, v130
	v_add_f32_e32 v131, v131, v59
	v_add_f32_e32 v122, v122, v74
	v_exp_f32_e32 v130, v130
	v_mul_f32_e32 v131, 0xbfb8aa3b, v131
	v_mul_f32_e32 v122, 0xbfb8aa3b, v122
	v_add_f32_e32 v123, v123, v75
	v_exp_f32_e32 v131, v131
	v_exp_f32_e32 v122, v122
	v_mul_f32_e32 v123, 0xbfb8aa3b, v123
	v_add_f32_e32 v124, v124, v76
	v_exp_f32_e32 v123, v123
	v_mul_f32_e32 v124, 0xbfb8aa3b, v124
	v_add_f32_e32 v125, v125, v77
	v_add_f32_e32 v114, v114, v58
	v_exp_f32_e32 v124, v124
	v_mul_f32_e32 v125, 0xbfb8aa3b, v125
	v_mul_f32_e32 v114, 0xbfb8aa3b, v114
	v_add_f32_e32 v115, v115, v59
	v_add_f32_e32 v106, v106, v74
	v_add_f32_e32 v130, 1.0, v130
	v_exp_f32_e32 v125, v125
	v_exp_f32_e32 v114, v114
	v_mul_f32_e32 v115, 0xbfb8aa3b, v115
	v_mul_f32_e32 v106, 0xbfb8aa3b, v106
	v_add_f32_e32 v107, v107, v75
	v_rcp_f32_e32 v130, v130
	v_add_f32_e32 v131, 1.0, v131
	v_add_f32_e32 v122, 1.0, v122
	v_exp_f32_e32 v115, v115
	v_exp_f32_e32 v106, v106
	v_mul_f32_e32 v107, 0xbfb8aa3b, v107
	v_add_f32_e32 v108, v108, v76
	v_rcp_f32_e32 v131, v131
	v_rcp_f32_e32 v122, v122
	v_add_f32_e32 v123, 1.0, v123
	v_exp_f32_e32 v107, v107
	v_mul_f32_e32 v108, 0xbfb8aa3b, v108
	v_add_f32_e32 v109, v109, v77
	v_add_f32_e32 v98, v98, v58
	v_rcp_f32_e32 v123, v123
	v_add_f32_e32 v124, 1.0, v124
	v_exp_f32_e32 v108, v108
	v_mul_f32_e32 v109, 0xbfb8aa3b, v109
	v_mul_f32_e32 v98, 0xbfb8aa3b, v98
	v_add_f32_e32 v99, v99, v59
	v_add_f32_e32 v90, v90, v74
	v_rcp_f32_e32 v124, v124
	v_add_f32_e32 v125, 1.0, v125
	v_add_f32_e32 v114, 1.0, v114
	v_exp_f32_e32 v109, v109
	v_exp_f32_e32 v98, v98
	v_mul_f32_e32 v99, 0xbfb8aa3b, v99
	v_mul_f32_e32 v90, 0xbfb8aa3b, v90
	v_add_f32_e32 v91, v91, v75
	v_mul_f32_e32 v138, v138, v130
	v_add_f32_e32 v130, v139, v67
	v_rcp_f32_e32 v125, v125
	v_rcp_f32_e32 v114, v114
	v_add_f32_e32 v115, 1.0, v115
	v_add_f32_e32 v106, 1.0, v106
	v_exp_f32_e32 v99, v99
	v_exp_f32_e32 v90, v90
	v_mul_f32_e32 v91, 0xbfb8aa3b, v91
	v_add_f32_e32 v92, v92, v76
	v_mul_f32_e32 v139, v130, v131
	v_add_f32_e32 v131, v132, v60
	v_mul_f32_e32 v122, v126, v122
	v_add_f32_e32 v126, v127, v79
	v_rcp_f32_e32 v115, v115
	v_rcp_f32_e32 v106, v106
	v_add_f32_e32 v107, 1.0, v107
	v_exp_f32_e32 v91, v91
	v_mul_f32_e32 v92, 0xbfb8aa3b, v92
	v_add_f32_e32 v93, v93, v77
	v_add_f32_e32 v82, v82, v58
	v_mul_f32_e32 v131, 0xbfb8aa3b, v131
	v_mul_f32_e32 v123, v126, v123
	v_add_f32_e32 v126, v128, v80
	v_rcp_f32_e32 v107, v107
	v_add_f32_e32 v108, 1.0, v108
	v_exp_f32_e32 v92, v92
	v_mul_f32_e32 v93, 0xbfb8aa3b, v93
	v_mul_f32_e32 v82, 0xbfb8aa3b, v82
	v_add_f32_e32 v83, v83, v59
	v_add_f32_e32 v50, v50, v58
	v_exp_f32_e32 v131, v131
	v_mul_f32_e32 v124, v126, v124
	v_add_f32_e32 v126, v129, v81
	v_add_f32_e32 v118, v118, v66
	v_rcp_f32_e32 v108, v108
	v_add_f32_e32 v109, 1.0, v109
	v_add_f32_e32 v98, 1.0, v98
	v_exp_f32_e32 v93, v93
	v_exp_f32_e32 v82, v82
	v_mul_f32_e32 v83, 0xbfb8aa3b, v83
	v_mul_f32_e32 v50, 0xbfb8aa3b, v50
	v_add_f32_e32 v51, v51, v59
	v_mul_f32_e32 v125, v126, v125
	v_mul_f32_e32 v126, v118, v114
	v_add_f32_e32 v114, v119, v67
	v_add_f32_e32 v110, v110, v78
	v_rcp_f32_e32 v109, v109
	v_rcp_f32_e32 v98, v98
	v_add_f32_e32 v99, 1.0, v99
	v_add_f32_e32 v90, 1.0, v90
	v_exp_f32_e32 v83, v83
	v_exp_f32_e32 v50, v50
	v_mul_f32_e32 v51, 0xbfb8aa3b, v51
	v_add_f32_e32 v34, v34, v58
	v_mul_f32_e32 v127, v114, v115
	v_add_f32_e32 v115, v116, v60
	v_mul_f32_e32 v106, v110, v106
	v_add_f32_e32 v110, v111, v79
	v_rcp_f32_e32 v99, v99
	v_rcp_f32_e32 v90, v90
	v_add_f32_e32 v91, 1.0, v91
	v_exp_f32_e32 v51, v51
	v_mul_f32_e32 v34, 0xbfb8aa3b, v34
	v_add_f32_e32 v35, v35, v59
	v_mul_f32_e32 v115, 0xbfb8aa3b, v115
	v_mul_f32_e32 v107, v110, v107
	v_add_f32_e32 v110, v112, v80
	v_rcp_f32_e32 v91, v91
	v_add_f32_e32 v92, 1.0, v92
	v_exp_f32_e32 v34, v34
	v_mul_f32_e32 v35, 0xbfb8aa3b, v35
	v_add_f32_e32 v18, v18, v58
	v_add_f32_e32 v131, 1.0, v131
	v_exp_f32_e32 v115, v115
	v_mul_f32_e32 v108, v110, v108
	v_add_f32_e32 v110, v113, v81
	v_add_f32_e32 v102, v102, v66
	v_rcp_f32_e32 v92, v92
	v_add_f32_e32 v93, 1.0, v93
	v_add_f32_e32 v82, 1.0, v82
	v_exp_f32_e32 v35, v35
	v_mul_f32_e32 v18, 0xbfb8aa3b, v18
	v_add_f32_e32 v19, v19, v59
	v_rcp_f32_e32 v131, v131
	v_mul_f32_e32 v109, v110, v109
	v_mul_f32_e32 v110, v102, v98
	v_add_f32_e32 v98, v103, v67
	v_add_f32_e32 v94, v94, v78
	v_rcp_f32_e32 v93, v93
	v_rcp_f32_e32 v82, v82
	v_add_f32_e32 v83, 1.0, v83
	v_add_f32_e32 v50, 1.0, v50
	v_exp_f32_e32 v18, v18
	v_mul_f32_e32 v19, 0xbfb8aa3b, v19
	v_add_f32_e32 v2, v2, v58
	v_mul_f32_e32 v111, v98, v99
	v_add_f32_e32 v99, v100, v60
	v_mul_f32_e32 v90, v94, v90
	v_add_f32_e32 v94, v95, v79
	v_rcp_f32_e32 v83, v83
	v_rcp_f32_e32 v50, v50
	v_add_f32_e32 v51, 1.0, v51
	v_exp_f32_e32 v19, v19
	v_mul_f32_e32 v2, 0xbfb8aa3b, v2
	v_add_f32_e32 v3, v3, v59
	v_add_f32_e32 v134, v134, v74
	v_mul_f32_e32 v99, 0xbfb8aa3b, v99
	v_mul_f32_e32 v91, v94, v91
	v_add_f32_e32 v94, v96, v80
	v_rcp_f32_e32 v51, v51
	v_add_f32_e32 v34, 1.0, v34
	v_exp_f32_e32 v2, v2
	v_mul_f32_e32 v3, 0xbfb8aa3b, v3
	v_mul_f32_e32 v134, 0xbfb8aa3b, v134
	v_add_f32_e32 v135, v135, v75
	v_add_f32_e32 v130, v140, v68
	v_add_f32_e32 v115, 1.0, v115
	v_exp_f32_e32 v99, v99
	v_mul_f32_e32 v92, v94, v92
	v_add_f32_e32 v94, v97, v81
	v_add_f32_e32 v86, v86, v66
	v_rcp_f32_e32 v34, v34
	v_add_f32_e32 v35, 1.0, v35
	v_exp_f32_e32 v3, v3
	v_exp_f32_e32 v134, v134
	v_mul_f32_e32 v135, 0xbfb8aa3b, v135
	v_add_f32_e32 v136, v136, v76
	v_mul_f32_e32 v140, v130, v131
	v_add_f32_e32 v131, v133, v61
	v_rcp_f32_e32 v115, v115
	v_mul_f32_e32 v93, v94, v93
	v_mul_f32_e32 v94, v86, v82
	v_add_f32_e32 v82, v87, v67
	v_add_f32_e32 v54, v54, v66
	v_rcp_f32_e32 v35, v35
	v_add_f32_e32 v18, 1.0, v18
	v_exp_f32_e32 v135, v135
	v_mul_f32_e32 v136, 0xbfb8aa3b, v136
	v_add_f32_e32 v137, v137, v77
	v_mul_f32_e32 v131, 0xbfb8aa3b, v131
	v_mul_f32_e32 v95, v82, v83
	v_add_f32_e32 v83, v84, v60
	v_mul_f32_e32 v54, v54, v50
	v_add_f32_e32 v50, v55, v67
	v_rcp_f32_e32 v18, v18
	v_add_f32_e32 v19, 1.0, v19
	v_exp_f32_e32 v136, v136
	v_mul_f32_e32 v137, 0xbfb8aa3b, v137
	v_exp_f32_e32 v131, v131
	v_mul_f32_e32 v83, 0xbfb8aa3b, v83
	v_mul_f32_e32 v55, v50, v51
	v_add_f32_e32 v51, v52, v60
	v_add_f32_e32 v38, v38, v66
	v_rcp_f32_e32 v19, v19
	v_add_f32_e32 v2, 1.0, v2
	v_exp_f32_e32 v137, v137
	v_add_f32_e32 v114, v120, v68
	v_add_f32_e32 v99, 1.0, v99
	v_exp_f32_e32 v83, v83
	v_mul_f32_e32 v51, 0xbfb8aa3b, v51
	v_mul_f32_e32 v38, v38, v34
	v_add_f32_e32 v34, v39, v67
	v_rcp_f32_e32 v2, v2
	v_add_f32_e32 v3, 1.0, v3
	v_add_f32_e32 v134, 1.0, v134
	v_mul_f32_e32 v120, v114, v115
	v_add_f32_e32 v115, v117, v61
	v_rcp_f32_e32 v99, v99
	v_exp_f32_e32 v51, v51
	v_mul_f32_e32 v39, v34, v35
	v_add_f32_e32 v35, v36, v60
	v_add_f32_e32 v22, v22, v66
	v_rcp_f32_e32 v3, v3
	v_rcp_f32_e32 v134, v134
	v_add_f32_e32 v135, 1.0, v135
	v_mul_f32_e32 v115, 0xbfb8aa3b, v115
	v_mul_f32_e32 v35, 0xbfb8aa3b, v35
	v_mul_f32_e32 v22, v22, v18
	v_add_f32_e32 v18, v23, v67
	v_rcp_f32_e32 v135, v135
	v_add_f32_e32 v136, 1.0, v136
	v_add_f32_e32 v131, 1.0, v131
	v_exp_f32_e32 v115, v115
	v_exp_f32_e32 v35, v35
	v_mul_f32_e32 v23, v18, v19
	v_add_f32_e32 v19, v20, v60
	v_add_f32_e32 v6, v6, v66
	v_rcp_f32_e32 v136, v136
	v_add_f32_e32 v137, 1.0, v137
	v_rcp_f32_e32 v131, v131
	v_add_f32_e32 v98, v104, v68
	v_add_f32_e32 v83, 1.0, v83
	v_mul_f32_e32 v19, 0xbfb8aa3b, v19
	v_mul_f32_e32 v6, v6, v2
	v_add_f32_e32 v2, v7, v67
	v_add_f32_e32 v142, v142, v78
	v_rcp_f32_e32 v137, v137
	v_mul_f32_e32 v104, v98, v99
	v_add_f32_e32 v99, v101, v61
	v_rcp_f32_e32 v83, v83
	v_add_f32_e32 v51, 1.0, v51
	v_exp_f32_e32 v19, v19
	v_mul_f32_e32 v7, v2, v3
	v_add_f32_e32 v3, v4, v60
	v_mul_f32_e32 v134, v142, v134
	v_add_f32_e32 v142, v143, v79
	v_mul_f32_e32 v99, 0xbfb8aa3b, v99
	v_rcp_f32_e32 v51, v51
	v_mul_f32_e32 v3, 0xbfb8aa3b, v3
	v_mul_f32_e32 v135, v142, v135
	v_add_f32_e32 v142, v144, v80
	v_add_f32_e32 v130, v141, v69
	v_add_f32_e32 v115, 1.0, v115
	v_exp_f32_e32 v99, v99
	v_add_f32_e32 v62, v62, v74
	v_add_f32_e32 v35, 1.0, v35
	v_exp_f32_e32 v3, v3
	v_mul_f32_e32 v136, v142, v136
	v_add_f32_e32 v142, v145, v81
	v_mul_f32_e32 v141, v130, v131
	v_lshl_add_u64 v[130:131], v[172:173], 0, v[182:183]
	v_cvt_pk_bf16_f32 v132, v134, v135
	v_rcp_f32_e32 v115, v115
	v_add_f32_e32 v82, v88, v68
	v_mul_f32_e32 v62, 0xbfb8aa3b, v62
	v_add_f32_e32 v63, v63, v75
	v_rcp_f32_e32 v35, v35
	v_mul_f32_e32 v137, v142, v137
	v_cvt_pk_bf16_f32 v133, v136, v137
	v_cvt_pk_bf16_f32 v134, v138, v139
	v_cvt_pk_bf16_f32 v135, v140, v141
	global_store_dwordx4 v[130:131], v[132:135], off
	v_mul_f32_e32 v88, v82, v83
	v_add_f32_e32 v83, v85, v61
	v_or_b32_e32 v132, 16, v174
	v_exp_f32_e32 v62, v62
	v_mul_f32_e32 v63, 0xbfb8aa3b, v63
	v_add_f32_e32 v64, v64, v76
	v_add_f32_e32 v50, v56, v68
	v_add_f32_e32 v42, v42, v74
	v_add_f32_e32 v19, 1.0, v19
	v_ashrrev_i32_e32 v133, 31, v132
	v_mul_f32_e32 v83, 0xbfb8aa3b, v83
	v_exp_f32_e32 v63, v63
	v_mul_f32_e32 v64, 0xbfb8aa3b, v64
	v_add_f32_e32 v65, v65, v77
	v_mul_f32_e32 v56, v50, v51
	v_add_f32_e32 v51, v53, v61
	v_mul_f32_e32 v42, 0xbfb8aa3b, v42
	v_add_f32_e32 v43, v43, v75
	v_rcp_f32_e32 v19, v19
	v_lshlrev_b64 v[132:133], 11, v[132:133]
	v_add_f32_e32 v114, v121, v69
	v_add_f32_e32 v99, 1.0, v99
	v_exp_f32_e32 v83, v83
	v_exp_f32_e32 v64, v64
	v_mul_f32_e32 v65, 0xbfb8aa3b, v65
	v_mul_f32_e32 v51, 0xbfb8aa3b, v51
	v_exp_f32_e32 v42, v42
	v_mul_f32_e32 v43, 0xbfb8aa3b, v43
	v_add_f32_e32 v44, v44, v76
	v_add_f32_e32 v34, v40, v68
	v_add_f32_e32 v26, v26, v74
	v_add_f32_e32 v3, 1.0, v3
	v_mul_f32_e32 v117, v114, v115
	v_lshl_add_u64 v[118:119], v[172:173], 0, v[132:133]
	v_cvt_pk_bf16_f32 v114, v122, v123
	v_rcp_f32_e32 v99, v99
	v_exp_f32_e32 v65, v65
	v_exp_f32_e32 v51, v51
	v_exp_f32_e32 v43, v43
	v_mul_f32_e32 v44, 0xbfb8aa3b, v44
	v_add_f32_e32 v45, v45, v77
	v_mul_f32_e32 v40, v34, v35
	v_add_f32_e32 v35, v37, v61
	v_mul_f32_e32 v26, 0xbfb8aa3b, v26
	v_add_f32_e32 v27, v27, v75
	v_rcp_f32_e32 v3, v3
	v_cvt_pk_bf16_f32 v115, v124, v125
	v_cvt_pk_bf16_f32 v116, v126, v127
	v_cvt_pk_bf16_f32 v117, v120, v117
	global_store_dwordx4 v[118:119], v[114:117], off
	v_add_f32_e32 v62, 1.0, v62
	v_exp_f32_e32 v44, v44
	v_or_b32_e32 v114, 32, v174
	v_mul_f32_e32 v45, 0xbfb8aa3b, v45
	v_mul_f32_e32 v35, 0xbfb8aa3b, v35
	v_exp_f32_e32 v26, v26
	v_mul_f32_e32 v27, 0xbfb8aa3b, v27
	v_add_f32_e32 v28, v28, v76
	v_add_f32_e32 v18, v24, v68
	v_add_f32_e32 v10, v10, v74
	v_ashrrev_i32_e32 v115, 31, v114
	v_rcp_f32_e32 v62, v62
	v_add_f32_e32 v63, 1.0, v63
	v_exp_f32_e32 v45, v45
	v_exp_f32_e32 v35, v35
	v_exp_f32_e32 v27, v27
	v_mul_f32_e32 v28, 0xbfb8aa3b, v28
	v_add_f32_e32 v29, v29, v77
	v_mul_f32_e32 v24, v18, v19
	v_add_f32_e32 v19, v21, v61
	v_mul_f32_e32 v10, 0xbfb8aa3b, v10
	v_add_f32_e32 v11, v11, v75
	v_lshlrev_b64 v[114:115], 11, v[114:115]
	v_add_f32_e32 v98, v105, v69
	v_add_f32_e32 v83, 1.0, v83
	v_rcp_f32_e32 v63, v63
	v_add_f32_e32 v64, 1.0, v64
	v_add_f32_e32 v42, 1.0, v42
	v_exp_f32_e32 v28, v28
	v_mul_f32_e32 v29, 0xbfb8aa3b, v29
	v_mul_f32_e32 v19, 0xbfb8aa3b, v19
	v_exp_f32_e32 v10, v10
	v_mul_f32_e32 v11, 0xbfb8aa3b, v11
	v_add_f32_e32 v12, v12, v76
	v_add_f32_e32 v2, v8, v68
	v_mul_f32_e32 v101, v98, v99
	v_lshl_add_u64 v[102:103], v[172:173], 0, v[114:115]
	v_cvt_pk_bf16_f32 v98, v106, v107
	v_rcp_f32_e32 v83, v83
	v_rcp_f32_e32 v64, v64
	v_add_f32_e32 v65, 1.0, v65
	v_add_f32_e32 v51, 1.0, v51
	v_rcp_f32_e32 v42, v42
	v_add_f32_e32 v43, 1.0, v43
	v_exp_f32_e32 v29, v29
	v_exp_f32_e32 v19, v19
	v_exp_f32_e32 v11, v11
	v_mul_f32_e32 v12, 0xbfb8aa3b, v12
	v_add_f32_e32 v13, v13, v77
	v_mul_f32_e32 v8, v2, v3
	v_add_f32_e32 v3, v5, v61
	v_cvt_pk_bf16_f32 v99, v108, v109
	v_cvt_pk_bf16_f32 v100, v110, v111
	v_cvt_pk_bf16_f32 v101, v104, v101
	global_store_dwordx4 v[102:103], v[98:101], off
	v_add_f32_e32 v70, v70, v78
	v_rcp_f32_e32 v65, v65
	v_or_b32_e32 v98, 48, v174
	v_rcp_f32_e32 v51, v51
	v_rcp_f32_e32 v43, v43
	v_add_f32_e32 v44, 1.0, v44
	v_add_f32_e32 v26, 1.0, v26
	v_exp_f32_e32 v12, v12
	v_mul_f32_e32 v13, 0xbfb8aa3b, v13
	v_mul_f32_e32 v3, 0xbfb8aa3b, v3
	v_ashrrev_i32_e32 v99, 31, v98
	v_mul_f32_e32 v62, v70, v62
	v_add_f32_e32 v70, v71, v79
	v_rcp_f32_e32 v44, v44
	v_add_f32_e32 v45, 1.0, v45
	v_add_f32_e32 v35, 1.0, v35
	v_rcp_f32_e32 v26, v26
	v_add_f32_e32 v27, 1.0, v27
	v_exp_f32_e32 v13, v13
	v_exp_f32_e32 v3, v3
	v_lshlrev_b64 v[98:99], 11, v[98:99]
	v_add_f32_e32 v82, v89, v69
	v_mul_f32_e32 v63, v70, v63
	v_add_f32_e32 v70, v72, v80
	v_add_f32_e32 v46, v46, v78
	v_rcp_f32_e32 v45, v45
	v_rcp_f32_e32 v35, v35
	v_rcp_f32_e32 v27, v27
	v_add_f32_e32 v28, 1.0, v28
	v_add_f32_e32 v10, 1.0, v10
	v_mul_f32_e32 v85, v82, v83
	v_lshl_add_u64 v[86:87], v[172:173], 0, v[98:99]
	v_mul_f32_e32 v64, v70, v64
	v_add_f32_e32 v70, v73, v81
	v_add_f32_e32 v50, v57, v69
	v_mul_f32_e32 v42, v46, v42
	v_add_f32_e32 v46, v47, v79
	v_rcp_f32_e32 v28, v28
	v_add_f32_e32 v29, 1.0, v29
	v_add_f32_e32 v19, 1.0, v19
	v_rcp_f32_e32 v10, v10
	v_add_f32_e32 v11, 1.0, v11
	v_cvt_pk_bf16_f32 v82, v90, v91
	v_cvt_pk_bf16_f32 v83, v92, v93
	v_cvt_pk_bf16_f32 v84, v94, v95
	v_cvt_pk_bf16_f32 v85, v88, v85
	global_store_dwordx4 v[86:87], v[82:85], off
	v_mul_f32_e32 v65, v70, v65
	v_mul_f32_e32 v53, v50, v51
	v_cvt_pk_bf16_f32 v50, v62, v63
	v_cvt_pk_bf16_f32 v51, v64, v65
	v_cvt_pk_bf16_f32 v52, v54, v55
	v_add_co_u32_e32 v54, vcc, s67, v130
	v_mul_f32_e32 v43, v46, v43
	v_add_f32_e32 v46, v48, v80
	v_add_f32_e32 v30, v30, v78
	v_rcp_f32_e32 v29, v29
	v_rcp_f32_e32 v19, v19
	v_rcp_f32_e32 v11, v11
	v_add_f32_e32 v12, 1.0, v12
	v_addc_co_u32_e32 v55, vcc, 0, v131, vcc
	v_mul_f32_e32 v44, v46, v44
	v_add_f32_e32 v46, v49, v81
	v_add_f32_e32 v34, v41, v69
	v_mul_f32_e32 v26, v30, v26
	v_add_f32_e32 v30, v31, v79
	v_rcp_f32_e32 v12, v12
	v_add_f32_e32 v13, 1.0, v13
	v_add_f32_e32 v3, 1.0, v3
	v_cvt_pk_bf16_f32 v53, v56, v53
	global_store_dwordx4 v[54:55], v[50:53], off
	v_mul_f32_e32 v45, v46, v45
	v_mul_f32_e32 v37, v34, v35
	v_cvt_pk_bf16_f32 v34, v42, v43
	v_cvt_pk_bf16_f32 v35, v44, v45
	v_cvt_pk_bf16_f32 v36, v38, v39
	v_add_co_u32_e32 v38, vcc, s68, v130
	v_mul_f32_e32 v27, v30, v27
	v_add_f32_e32 v30, v32, v80
	v_add_f32_e32 v14, v14, v78
	v_rcp_f32_e32 v13, v13
	v_rcp_f32_e32 v3, v3
	v_addc_co_u32_e32 v39, vcc, 0, v131, vcc
	v_mul_f32_e32 v28, v30, v28
	v_add_f32_e32 v30, v33, v81
	v_add_f32_e32 v18, v25, v69
	v_mul_f32_e32 v10, v14, v10
	v_add_f32_e32 v14, v15, v79
	v_cvt_pk_bf16_f32 v37, v40, v37
	global_store_dwordx4 v[38:39], v[34:37], off
	v_mul_f32_e32 v29, v30, v29
	v_mul_f32_e32 v21, v18, v19
	v_cvt_pk_bf16_f32 v18, v26, v27
	v_cvt_pk_bf16_f32 v19, v28, v29
	v_cvt_pk_bf16_f32 v20, v22, v23
	v_add_co_u32_e32 v22, vcc, s2, v130
	v_mul_f32_e32 v11, v14, v11
	v_add_f32_e32 v14, v16, v80
	v_addc_co_u32_e32 v23, vcc, 0, v131, vcc
	v_mul_f32_e32 v12, v14, v12
	v_add_f32_e32 v14, v17, v81
	v_add_f32_e32 v2, v9, v69
	v_cvt_pk_bf16_f32 v21, v24, v21
	global_store_dwordx4 v[22:23], v[18:21], off
	v_mul_f32_e32 v13, v14, v13
	v_mul_f32_e32 v5, v2, v3
	v_cvt_pk_bf16_f32 v2, v10, v11
	v_cvt_pk_bf16_f32 v3, v12, v13
	v_cvt_pk_bf16_f32 v4, v6, v7
	v_add_co_u32_e32 v6, vcc, 0x58000, v130
	s_mov_b32 s2, s48
	s_nop 0
	v_addc_co_u32_e32 v7, vcc, 0, v131, vcc
	s_and_b64 vcc, exec, s[38:39]
	v_cvt_pk_bf16_f32 v5, v8, v5
	global_store_dwordx4 v[6:7], v[2:5], off
	s_cbranch_vccz .LBB0_88
	s_waitcnt vmcnt(8)
	s_cmpk_gt_u32 s35, 0xff
	s_cbranch_scc1 .LBB0_99
	s_barrier

.Lkprio_3:
.LBB0_260:
	s_add_u32 s22, s0, 0xfffc0080
	s_addc_u32 s23, s1, -1
	s_add_i32 s60, 0, 0x10000
	v_add_u32_e32 v142, s60, v178
	ds_read_b128 v[130:133], v142
	ds_read_b128 v[134:137], v142 offset:1024
	ds_read_b128 v[138:141], v142 offset:2048
	ds_read_b128 v[142:145], v142 offset:3072
	s_cmp_eq_u32 s59, 12
	s_cselect_b32 s47, s35, s23
	s_cselect_b32 s46, s55, s22
	s_cselect_b32 s23, s31, s58
	s_cselect_b32 s22, s56, s57
	v_lshl_add_u64 v[186:187], s[0:1], 0, v[168:169]
	s_add_i32 m0, s27, 0xc000
	ds_read_b128 v[172:175], v180
	ds_read_b128 v[182:185], v180 offset:1024
	ds_read_b128 v[206:209], v180 offset:2048
	ds_read_b128 v[210:213], v180 offset:3072
	ds_read_b128 v[214:217], v180 offset:4096
	ds_read_b128 v[218:221], v180 offset:5120
	ds_read_b128 v[222:225], v180 offset:6144
	ds_read_b128 v[226:229], v180 offset:7168
	global_load_lds_dwordx4 v[186:187], off
	s_add_i32 m0, s27, 0xe000
	v_lshl_add_u64 v[186:187], s[0:1], 0, v[170:171]
	global_load_lds_dwordx4 v[186:187], off
	s_waitcnt lgkmcnt(8)
	s_barrier
	s_waitcnt lgkmcnt(0)
	v_mfma_f32_16x16x32_bf16 v[126:129], v[130:133], v[172:175], v[126:129]
	v_mfma_f32_16x16x32_bf16 v[122:125], v[138:141], v[172:175], v[122:125]
	v_mfma_f32_16x16x32_bf16 v[110:113], v[130:133], v[206:209], v[110:113]
	v_mfma_f32_16x16x32_bf16 v[106:109], v[138:141], v[206:209], v[106:109]
	v_mfma_f32_16x16x32_bf16 v[94:97], v[130:133], v[214:217], v[94:97]
	v_mfma_f32_16x16x32_bf16 v[90:93], v[138:141], v[214:217], v[90:93]
	v_mfma_f32_16x16x32_bf16 v[78:81], v[130:133], v[222:225], v[78:81]
	v_mfma_f32_16x16x32_bf16 v[74:77], v[138:141], v[222:225], v[74:77]
	v_mfma_f32_16x16x32_bf16 v[126:129], v[134:137], v[182:185], v[126:129]
	v_mfma_f32_16x16x32_bf16 v[122:125], v[142:145], v[182:185], v[122:125]
	v_mfma_f32_16x16x32_bf16 v[110:113], v[134:137], v[210:213], v[110:113]
	v_mfma_f32_16x16x32_bf16 v[106:109], v[142:145], v[210:213], v[106:109]
	v_mfma_f32_16x16x32_bf16 v[94:97], v[134:137], v[218:221], v[94:97]
	v_mfma_f32_16x16x32_bf16 v[90:93], v[142:145], v[218:221], v[90:93]
	v_mfma_f32_16x16x32_bf16 v[78:81], v[134:137], v[226:229], v[78:81]
	v_mfma_f32_16x16x32_bf16 v[74:77], v[142:145], v[226:229], v[74:77]
	s_barrier
	s_add_i32 s62, 0, 0x14000
	s_add_i32 s60, s60, s25
	v_add_u32_e32 v181, s62, v178
	v_lshl_add_u64 v[186:187], s[22:23], 0, v[0:1]
	s_mov_b32 m0, s60
	ds_read_b128 v[230:233], v181
	ds_read_b128 v[234:237], v181 offset:1024
	ds_read_b128 v[238:241], v181 offset:2048
	ds_read_b128 v[242:245], v181 offset:3072
	global_load_lds_dwordx4 v[186:187], off
	s_add_i32 m0, s60, 0x2000
	v_lshl_add_u64 v[246:247], s[22:23], 0, v[162:163]
	global_load_lds_dwordx4 v[246:247], off
	s_barrier
	s_waitcnt lgkmcnt(0)
	v_mfma_f32_16x16x32_bf16 v[118:121], v[230:233], v[172:175], v[118:121]
	v_mfma_f32_16x16x32_bf16 v[114:117], v[238:241], v[172:175], v[114:117]
	v_mfma_f32_16x16x32_bf16 v[102:105], v[230:233], v[206:209], v[102:105]
	v_mfma_f32_16x16x32_bf16 v[98:101], v[238:241], v[206:209], v[98:101]
	v_mfma_f32_16x16x32_bf16 v[86:89], v[230:233], v[214:217], v[86:89]
	v_mfma_f32_16x16x32_bf16 v[82:85], v[238:241], v[214:217], v[82:85]
	v_mfma_f32_16x16x32_bf16 v[70:73], v[230:233], v[222:225], v[70:73]
	v_mfma_f32_16x16x32_bf16 v[66:69], v[238:241], v[222:225], v[66:69]
	v_mfma_f32_16x16x32_bf16 v[118:121], v[234:237], v[182:185], v[118:121]
	v_mfma_f32_16x16x32_bf16 v[114:117], v[242:245], v[182:185], v[114:117]
	v_mfma_f32_16x16x32_bf16 v[102:105], v[234:237], v[210:213], v[102:105]
	v_mfma_f32_16x16x32_bf16 v[98:101], v[242:245], v[210:213], v[98:101]
	v_mfma_f32_16x16x32_bf16 v[86:89], v[234:237], v[218:221], v[86:89]
	v_mfma_f32_16x16x32_bf16 v[82:85], v[242:245], v[218:221], v[82:85]
	v_mfma_f32_16x16x32_bf16 v[70:73], v[234:237], v[226:229], v[70:73]
	v_mfma_f32_16x16x32_bf16 v[66:69], v[242:245], v[226:229], v[66:69]
	s_barrier
	s_mov_b32 m0, s27
	v_lshl_add_u64 v[248:249], s[46:47], 0, v[166:167]
	ds_read_b128 v[172:175], v180 offset:16384
	ds_read_b128 v[182:185], v180 offset:17408
	ds_read_b128 v[206:209], v180 offset:18432
	ds_read_b128 v[210:213], v180 offset:19456
	ds_read_b128 v[214:217], v180 offset:20480
	ds_read_b128 v[218:221], v180 offset:21504
	ds_read_b128 v[222:225], v180 offset:22528
	ds_read_b128 v[226:229], v180 offset:23552
	global_load_lds_dwordx4 v[248:249], off
	s_mov_b32 m0, s45
	v_lshl_add_u64 v[250:251], s[46:47], 0, v[164:165]
	global_load_lds_dwordx4 v[250:251], off
	s_barrier
	s_waitcnt lgkmcnt(0)
	v_mfma_f32_16x16x32_bf16 v[62:65], v[130:133], v[172:175], v[62:65]
	v_mfma_f32_16x16x32_bf16 v[58:61], v[138:141], v[172:175], v[58:61]
	v_mfma_f32_16x16x32_bf16 v[50:53], v[130:133], v[206:209], v[50:53]
	v_mfma_f32_16x16x32_bf16 v[42:45], v[138:141], v[206:209], v[42:45]
	v_mfma_f32_16x16x32_bf16 v[34:37], v[130:133], v[214:217], v[34:37]
	v_mfma_f32_16x16x32_bf16 v[26:29], v[138:141], v[214:217], v[26:29]
	v_mfma_f32_16x16x32_bf16 v[18:21], v[130:133], v[222:225], v[18:21]
	v_mfma_f32_16x16x32_bf16 v[10:13], v[138:141], v[222:225], v[10:13]
	v_mfma_f32_16x16x32_bf16 v[62:65], v[134:137], v[182:185], v[62:65]
	v_mfma_f32_16x16x32_bf16 v[58:61], v[142:145], v[182:185], v[58:61]
	v_mfma_f32_16x16x32_bf16 v[50:53], v[134:137], v[210:213], v[50:53]
	v_mfma_f32_16x16x32_bf16 v[42:45], v[142:145], v[210:213], v[42:45]
	v_mfma_f32_16x16x32_bf16 v[34:37], v[134:137], v[218:221], v[34:37]
	v_mfma_f32_16x16x32_bf16 v[26:29], v[142:145], v[218:221], v[26:29]
	v_mfma_f32_16x16x32_bf16 v[18:21], v[134:137], v[226:229], v[18:21]
	v_mfma_f32_16x16x32_bf16 v[10:13], v[142:145], v[226:229], v[10:13]
	s_barrier
	s_add_u32 s60, s22, 0x40000
	s_addc_u32 s61, s23, 0
	s_add_i32 s62, s62, s25
	s_mov_b32 m0, s62
	s_nop 0
	global_load_lds_dwordx4 v0, s[60:61]
	s_add_i32 m0, s62, 0x2000
	v_lshl_add_u64 v[130:131], s[60:61], 0, v[162:163]
	global_load_lds_dwordx4 v[130:131], off
	s_waitcnt vmcnt(6)
	s_barrier
	v_mfma_f32_16x16x32_bf16 v[54:57], v[230:233], v[172:175], v[54:57]
	v_mfma_f32_16x16x32_bf16 v[46:49], v[238:241], v[172:175], v[46:49]
	v_mfma_f32_16x16x32_bf16 v[38:41], v[230:233], v[206:209], v[38:41]
	v_mfma_f32_16x16x32_bf16 v[30:33], v[238:241], v[206:209], v[30:33]
	v_mfma_f32_16x16x32_bf16 v[22:25], v[230:233], v[214:217], v[22:25]
	v_mfma_f32_16x16x32_bf16 v[14:17], v[238:241], v[214:217], v[14:17]
	v_mfma_f32_16x16x32_bf16 v[6:9], v[230:233], v[222:225], v[6:9]
	v_mfma_f32_16x16x32_bf16 v[2:5], v[238:241], v[222:225], v[2:5]
	v_mfma_f32_16x16x32_bf16 v[54:57], v[234:237], v[182:185], v[54:57]
	v_mfma_f32_16x16x32_bf16 v[46:49], v[242:245], v[182:185], v[46:49]
	v_mfma_f32_16x16x32_bf16 v[38:41], v[234:237], v[210:213], v[38:41]
	v_mfma_f32_16x16x32_bf16 v[30:33], v[242:245], v[210:213], v[30:33]
	v_mfma_f32_16x16x32_bf16 v[22:25], v[234:237], v[218:221], v[22:25]
	v_mfma_f32_16x16x32_bf16 v[14:17], v[242:245], v[218:221], v[14:17]
	v_mfma_f32_16x16x32_bf16 v[6:9], v[234:237], v[226:229], v[6:9]
	v_mfma_f32_16x16x32_bf16 v[2:5], v[242:245], v[226:229], v[2:5]
	s_barrier
	s_add_i32 s60, 0, 0x18000
	v_add_u32_e32 v142, s60, v178
	ds_read_b128 v[130:133], v142
	ds_read_b128 v[134:137], v142 offset:1024
	ds_read_b128 v[138:141], v142 offset:2048
	ds_read_b128 v[142:145], v142 offset:3072
	s_add_u32 s46, s46, 0x40000
	s_addc_u32 s47, s47, 0
	s_mov_b32 m0, s48
	v_lshl_add_u64 v[230:231], s[46:47], 0, v[166:167]
	ds_read_b128 v[172:175], v180 offset:32768
	ds_read_b128 v[182:185], v180 offset:33792
	ds_read_b128 v[206:209], v180 offset:34816
	ds_read_b128 v[210:213], v180 offset:35840
	ds_read_b128 v[214:217], v180 offset:36864
	ds_read_b128 v[218:221], v180 offset:37888
	ds_read_b128 v[222:225], v180 offset:38912
	ds_read_b128 v[226:229], v180 offset:39936
	global_load_lds_dwordx4 v[230:231], off
	s_mov_b32 m0, s49
	v_lshl_add_u64 v[230:231], s[46:47], 0, v[164:165]
	global_load_lds_dwordx4 v[230:231], off
	s_waitcnt lgkmcnt(8)
	s_barrier
	s_waitcnt lgkmcnt(0)
	v_mfma_f32_16x16x32_bf16 v[126:129], v[130:133], v[172:175], v[126:129]
	v_mfma_f32_16x16x32_bf16 v[122:125], v[138:141], v[172:175], v[122:125]
	v_mfma_f32_16x16x32_bf16 v[110:113], v[130:133], v[206:209], v[110:113]
	v_mfma_f32_16x16x32_bf16 v[106:109], v[138:141], v[206:209], v[106:109]
	v_mfma_f32_16x16x32_bf16 v[94:97], v[130:133], v[214:217], v[94:97]
	v_mfma_f32_16x16x32_bf16 v[90:93], v[138:141], v[214:217], v[90:93]
	v_mfma_f32_16x16x32_bf16 v[78:81], v[130:133], v[222:225], v[78:81]
	v_mfma_f32_16x16x32_bf16 v[74:77], v[138:141], v[222:225], v[74:77]
	v_mfma_f32_16x16x32_bf16 v[126:129], v[134:137], v[182:185], v[126:129]
	v_mfma_f32_16x16x32_bf16 v[122:125], v[142:145], v[182:185], v[122:125]
	v_mfma_f32_16x16x32_bf16 v[110:113], v[134:137], v[210:213], v[110:113]
	v_mfma_f32_16x16x32_bf16 v[106:109], v[142:145], v[210:213], v[106:109]
	v_mfma_f32_16x16x32_bf16 v[94:97], v[134:137], v[218:221], v[94:97]
	v_mfma_f32_16x16x32_bf16 v[90:93], v[142:145], v[218:221], v[90:93]
	v_mfma_f32_16x16x32_bf16 v[78:81], v[134:137], v[226:229], v[78:81]
	v_mfma_f32_16x16x32_bf16 v[74:77], v[142:145], v[226:229], v[74:77]
	s_barrier
	s_add_i32 s46, 0, 0x1c000
	s_add_i32 s47, s60, s25
	v_add_u32_e32 v181, s46, v178
	v_lshl_add_u64 v[186:187], v[186:187], 0, s[94:95]
	s_mov_b32 m0, s47
	ds_read_b128 v[230:233], v181
	ds_read_b128 v[234:237], v181 offset:1024
	ds_read_b128 v[238:241], v181 offset:2048
	ds_read_b128 v[242:245], v181 offset:3072
	global_load_lds_dwordx4 v[186:187], off
	s_add_i32 m0, s47, 0x2000
	v_lshl_add_u64 v[186:187], v[246:247], 0, s[94:95]
	global_load_lds_dwordx4 v[186:187], off
	s_barrier
	s_waitcnt lgkmcnt(0)
	v_mfma_f32_16x16x32_bf16 v[118:121], v[230:233], v[172:175], v[118:121]
	v_mfma_f32_16x16x32_bf16 v[114:117], v[238:241], v[172:175], v[114:117]
	v_mfma_f32_16x16x32_bf16 v[102:105], v[230:233], v[206:209], v[102:105]
	v_mfma_f32_16x16x32_bf16 v[98:101], v[238:241], v[206:209], v[98:101]
	v_mfma_f32_16x16x32_bf16 v[86:89], v[230:233], v[214:217], v[86:89]
	v_mfma_f32_16x16x32_bf16 v[82:85], v[238:241], v[214:217], v[82:85]
	v_mfma_f32_16x16x32_bf16 v[70:73], v[230:233], v[222:225], v[70:73]
	v_mfma_f32_16x16x32_bf16 v[66:69], v[238:241], v[222:225], v[66:69]
	v_mfma_f32_16x16x32_bf16 v[118:121], v[234:237], v[182:185], v[118:121]
	v_mfma_f32_16x16x32_bf16 v[114:117], v[242:245], v[182:185], v[114:117]
	v_mfma_f32_16x16x32_bf16 v[102:105], v[234:237], v[210:213], v[102:105]
	v_mfma_f32_16x16x32_bf16 v[98:101], v[242:245], v[210:213], v[98:101]
	v_mfma_f32_16x16x32_bf16 v[86:89], v[234:237], v[218:221], v[86:89]
	v_mfma_f32_16x16x32_bf16 v[82:85], v[242:245], v[218:221], v[82:85]
	v_mfma_f32_16x16x32_bf16 v[70:73], v[234:237], v[226:229], v[70:73]
	v_mfma_f32_16x16x32_bf16 v[66:69], v[242:245], v[226:229], v[66:69]
	s_barrier
	s_mov_b32 m0, s51
	v_lshl_add_u64 v[186:187], v[248:249], 0, s[94:95]
	ds_read_b128 v[172:175], v180 offset:49152
	ds_read_b128 v[182:185], v180 offset:50176
	ds_read_b128 v[206:209], v180 offset:51200
	ds_read_b128 v[210:213], v180 offset:52224
	ds_read_b128 v[214:217], v180 offset:53248
	ds_read_b128 v[218:221], v180 offset:54272
	ds_read_b128 v[222:225], v180 offset:55296
	ds_read_b128 v[226:229], v180 offset:56320
	global_load_lds_dwordx4 v[186:187], off
	s_mov_b32 m0, s52
	v_lshl_add_u64 v[186:187], v[250:251], 0, s[94:95]
	global_load_lds_dwordx4 v[186:187], off
	s_barrier
	s_waitcnt lgkmcnt(0)
	v_mfma_f32_16x16x32_bf16 v[62:65], v[130:133], v[172:175], v[62:65]
	v_mfma_f32_16x16x32_bf16 v[58:61], v[138:141], v[172:175], v[58:61]
	v_mfma_f32_16x16x32_bf16 v[50:53], v[130:133], v[206:209], v[50:53]
	v_mfma_f32_16x16x32_bf16 v[42:45], v[138:141], v[206:209], v[42:45]
	v_mfma_f32_16x16x32_bf16 v[34:37], v[130:133], v[214:217], v[34:37]
	v_mfma_f32_16x16x32_bf16 v[26:29], v[138:141], v[214:217], v[26:29]
	v_mfma_f32_16x16x32_bf16 v[18:21], v[130:133], v[222:225], v[18:21]
	v_mfma_f32_16x16x32_bf16 v[10:13], v[138:141], v[222:225], v[10:13]
	v_mfma_f32_16x16x32_bf16 v[62:65], v[134:137], v[182:185], v[62:65]
	v_mfma_f32_16x16x32_bf16 v[58:61], v[142:145], v[182:185], v[58:61]
	v_mfma_f32_16x16x32_bf16 v[50:53], v[134:137], v[210:213], v[50:53]
	v_mfma_f32_16x16x32_bf16 v[42:45], v[142:145], v[210:213], v[42:45]
	v_mfma_f32_16x16x32_bf16 v[34:37], v[134:137], v[218:221], v[34:37]
	v_mfma_f32_16x16x32_bf16 v[26:29], v[142:145], v[218:221], v[26:29]
	v_mfma_f32_16x16x32_bf16 v[18:21], v[134:137], v[226:229], v[18:21]
	v_mfma_f32_16x16x32_bf16 v[10:13], v[142:145], v[226:229], v[10:13]
	s_barrier
	s_add_u32 s22, s22, 0x40080
	s_addc_u32 s23, s23, 0
	s_add_i32 s46, s46, s25
	s_mov_b32 m0, s46
	s_nop 0
	global_load_lds_dwordx4 v0, s[22:23]
	s_add_i32 m0, s46, 0x2000
	v_lshl_add_u64 v[130:131], s[22:23], 0, v[162:163]
	global_load_lds_dwordx4 v[130:131], off
	s_waitcnt vmcnt(6)
	s_barrier
	v_mfma_f32_16x16x32_bf16 v[54:57], v[230:233], v[172:175], v[54:57]
	v_mfma_f32_16x16x32_bf16 v[46:49], v[238:241], v[172:175], v[46:49]
	v_mfma_f32_16x16x32_bf16 v[38:41], v[230:233], v[206:209], v[38:41]
	v_mfma_f32_16x16x32_bf16 v[30:33], v[238:241], v[206:209], v[30:33]
	v_mfma_f32_16x16x32_bf16 v[22:25], v[230:233], v[214:217], v[22:25]
	v_mfma_f32_16x16x32_bf16 v[14:17], v[238:241], v[214:217], v[14:17]
	v_mfma_f32_16x16x32_bf16 v[6:9], v[230:233], v[222:225], v[6:9]
	v_mfma_f32_16x16x32_bf16 v[2:5], v[238:241], v[222:225], v[2:5]
	v_mfma_f32_16x16x32_bf16 v[54:57], v[234:237], v[182:185], v[54:57]
	v_mfma_f32_16x16x32_bf16 v[46:49], v[242:245], v[182:185], v[46:49]
	v_mfma_f32_16x16x32_bf16 v[38:41], v[234:237], v[210:213], v[38:41]
	v_mfma_f32_16x16x32_bf16 v[30:33], v[242:245], v[210:213], v[30:33]
	v_mfma_f32_16x16x32_bf16 v[22:25], v[234:237], v[218:221], v[22:25]
	v_mfma_f32_16x16x32_bf16 v[14:17], v[242:245], v[218:221], v[14:17]
	v_mfma_f32_16x16x32_bf16 v[6:9], v[234:237], v[226:229], v[6:9]
	v_mfma_f32_16x16x32_bf16 v[2:5], v[242:245], v[226:229], v[2:5]
	s_barrier
	s_add_i32 s59, s59, 2
	s_add_u32 s0, s0, 0x100
	s_addc_u32 s1, s1, 0
	s_add_u32 s57, s57, 0x100
	s_addc_u32 s58, s58, 0
	s_cmp_gt_u32 s59, 13
	s_cbranch_scc0 .LBB0_260
	v_lshl_or_b32 v172, s54, 8, v179
	v_ashrrev_i32_e32 v173, 31, v172
	v_cndmask_b32_e64 v131, 0, 1, s[2:3]
	v_lshl_add_u64 v[174:175], v[172:173], 2, s[8:9]
	v_mov_b32_e32 v130, 0
	v_cmp_ne_u32_e64 s[0:1], 1, v131
	s_andn2_b64 vcc, exec, s[2:3]
	v_mov_b32_e32 v134, 0
	v_mov_b32_e32 v135, 0
	v_mov_b32_e32 v136, 0
	v_mov_b32_e32 v137, 0
	s_cbranch_vccnz .LBB0_263
	global_load_dwordx4 v[134:137], v[174:175], off

.Lkprio_2:
.LBB0_331:
	s_add_u32 s22, s24, 0x100
	s_addc_u32 s23, s25, 0
	s_add_i32 s52, 0, 0x10000
	v_add_u32_e32 v140, s52, v144
	ds_read_b128 v[164:167], v140
	ds_read_b128 v[168:171], v140 offset:1024
	ds_read_b128 v[172:175], v140 offset:2048
	ds_read_b128 v[176:179], v140 offset:3072
	s_cmp_eq_u32 s51, 40
	s_cselect_b32 s29, s3, s23
	s_cselect_b32 s28, s2, s22
	s_cselect_b32 s27, s1, s41
	s_cselect_b32 s26, s0, s40
	v_lshl_add_u64 v[140:141], s[24:25], 0, v[136:137]
	s_add_i32 m0, s35, 0xc000
	ds_read_b128 v[180:183], v162
	ds_read_b128 v[184:187], v162 offset:1024
	ds_read_b128 v[206:209], v162 offset:2048
	ds_read_b128 v[210:213], v162 offset:3072
	ds_read_b128 v[214:217], v162 offset:4096
	ds_read_b128 v[218:221], v162 offset:5120
	ds_read_b128 v[222:225], v162 offset:6144
	ds_read_b128 v[226:229], v162 offset:7168
	global_load_lds_dwordx4 v[140:141], off
	s_add_i32 m0, s35, 0xe000
	v_lshl_add_u64 v[140:141], s[24:25], 0, v[138:139]
	global_load_lds_dwordx4 v[140:141], off
	s_waitcnt lgkmcnt(8)
	s_barrier
	s_waitcnt lgkmcnt(0)
	v_mfma_f32_16x16x32_bf16 v[126:129], v[164:167], v[180:183], v[126:129]
	v_mfma_f32_16x16x32_bf16 v[122:125], v[172:175], v[180:183], v[122:125]
	v_mfma_f32_16x16x32_bf16 v[114:117], v[164:167], v[206:209], v[114:117]
	v_mfma_f32_16x16x32_bf16 v[106:109], v[172:175], v[206:209], v[106:109]
	v_mfma_f32_16x16x32_bf16 v[98:101], v[164:167], v[214:217], v[98:101]
	v_mfma_f32_16x16x32_bf16 v[90:93], v[172:175], v[214:217], v[90:93]
	v_mfma_f32_16x16x32_bf16 v[82:85], v[164:167], v[222:225], v[82:85]
	v_mfma_f32_16x16x32_bf16 v[74:77], v[172:175], v[222:225], v[74:77]
	v_mfma_f32_16x16x32_bf16 v[126:129], v[168:171], v[184:187], v[126:129]
	v_mfma_f32_16x16x32_bf16 v[122:125], v[176:179], v[184:187], v[122:125]
	v_mfma_f32_16x16x32_bf16 v[114:117], v[168:171], v[210:213], v[114:117]
	v_mfma_f32_16x16x32_bf16 v[106:109], v[176:179], v[210:213], v[106:109]
	v_mfma_f32_16x16x32_bf16 v[98:101], v[168:171], v[218:221], v[98:101]
	v_mfma_f32_16x16x32_bf16 v[90:93], v[176:179], v[218:221], v[90:93]
	v_mfma_f32_16x16x32_bf16 v[82:85], v[168:171], v[226:229], v[82:85]
	v_mfma_f32_16x16x32_bf16 v[74:77], v[176:179], v[226:229], v[74:77]
	s_barrier
	s_add_i32 s53, 0, 0x14000
	v_add_u32_e32 v140, s53, v144
	s_add_i32 s24, s52, s31
	ds_read_b128 v[230:233], v140
	ds_read_b128 v[234:237], v140 offset:1024
	ds_read_b128 v[238:241], v140 offset:2048
	ds_read_b128 v[242:245], v140 offset:3072
	v_lshl_add_u64 v[140:141], s[26:27], 0, v[0:1]
	s_mov_b32 m0, s24
	v_lshl_add_u64 v[246:247], s[26:27], 0, v[130:131]
	global_load_lds_dwordx4 v[140:141], off
	s_add_i32 m0, s24, 0x2000
	s_nop 0
	global_load_lds_dwordx4 v[246:247], off
	s_barrier
	s_waitcnt lgkmcnt(0)
	v_mfma_f32_16x16x32_bf16 v[118:121], v[230:233], v[180:183], v[118:121]
	v_mfma_f32_16x16x32_bf16 v[110:113], v[238:241], v[180:183], v[110:113]
	v_mfma_f32_16x16x32_bf16 v[102:105], v[230:233], v[206:209], v[102:105]
	v_mfma_f32_16x16x32_bf16 v[94:97], v[238:241], v[206:209], v[94:97]
	v_mfma_f32_16x16x32_bf16 v[86:89], v[230:233], v[214:217], v[86:89]
	v_mfma_f32_16x16x32_bf16 v[78:81], v[238:241], v[214:217], v[78:81]
	v_mfma_f32_16x16x32_bf16 v[70:73], v[230:233], v[222:225], v[70:73]
	v_mfma_f32_16x16x32_bf16 v[66:69], v[238:241], v[222:225], v[66:69]
	v_mfma_f32_16x16x32_bf16 v[118:121], v[234:237], v[184:187], v[118:121]
	v_mfma_f32_16x16x32_bf16 v[110:113], v[242:245], v[184:187], v[110:113]
	v_mfma_f32_16x16x32_bf16 v[102:105], v[234:237], v[210:213], v[102:105]
	v_mfma_f32_16x16x32_bf16 v[94:97], v[242:245], v[210:213], v[94:97]
	v_mfma_f32_16x16x32_bf16 v[86:89], v[234:237], v[218:221], v[86:89]
	v_mfma_f32_16x16x32_bf16 v[78:81], v[242:245], v[218:221], v[78:81]
	v_mfma_f32_16x16x32_bf16 v[70:73], v[234:237], v[226:229], v[70:73]
	v_mfma_f32_16x16x32_bf16 v[66:69], v[242:245], v[226:229], v[66:69]
	s_barrier
	s_mov_b32 m0, s35
	v_lshl_add_u64 v[248:249], s[28:29], 0, v[134:135]
	ds_read_b128 v[180:183], v162 offset:16384
	ds_read_b128 v[184:187], v162 offset:17408
	ds_read_b128 v[206:209], v162 offset:18432
	ds_read_b128 v[210:213], v162 offset:19456
	ds_read_b128 v[214:217], v162 offset:20480
	ds_read_b128 v[218:221], v162 offset:21504
	ds_read_b128 v[222:225], v162 offset:22528
	ds_read_b128 v[226:229], v162 offset:23552
	global_load_lds_dwordx4 v[248:249], off
	s_mov_b32 m0, s36
	v_lshl_add_u64 v[250:251], s[28:29], 0, v[132:133]
	global_load_lds_dwordx4 v[250:251], off
	s_barrier
	s_waitcnt lgkmcnt(0)
	v_mfma_f32_16x16x32_bf16 v[62:65], v[164:167], v[180:183], v[62:65]
	v_mfma_f32_16x16x32_bf16 v[58:61], v[172:175], v[180:183], v[58:61]
	v_mfma_f32_16x16x32_bf16 v[50:53], v[164:167], v[206:209], v[50:53]
	v_mfma_f32_16x16x32_bf16 v[42:45], v[172:175], v[206:209], v[42:45]
	v_mfma_f32_16x16x32_bf16 v[34:37], v[164:167], v[214:217], v[34:37]
	v_mfma_f32_16x16x32_bf16 v[26:29], v[172:175], v[214:217], v[26:29]
	v_mfma_f32_16x16x32_bf16 v[18:21], v[164:167], v[222:225], v[18:21]
	v_mfma_f32_16x16x32_bf16 v[10:13], v[172:175], v[222:225], v[10:13]
	v_mfma_f32_16x16x32_bf16 v[62:65], v[168:171], v[184:187], v[62:65]
	v_mfma_f32_16x16x32_bf16 v[58:61], v[176:179], v[184:187], v[58:61]
	v_mfma_f32_16x16x32_bf16 v[50:53], v[168:171], v[210:213], v[50:53]
	v_mfma_f32_16x16x32_bf16 v[42:45], v[176:179], v[210:213], v[42:45]
	v_mfma_f32_16x16x32_bf16 v[34:37], v[168:171], v[218:221], v[34:37]
	v_mfma_f32_16x16x32_bf16 v[26:29], v[176:179], v[218:221], v[26:29]
	v_mfma_f32_16x16x32_bf16 v[18:21], v[168:171], v[226:229], v[18:21]
	v_mfma_f32_16x16x32_bf16 v[10:13], v[176:179], v[226:229], v[10:13]
	s_barrier
	s_add_u32 s24, s26, 0xb0000
	s_addc_u32 s25, s27, 0
	s_add_i32 s52, s53, s31
	s_mov_b32 m0, s52
	s_nop 0
	global_load_lds_dwordx4 v0, s[24:25]
	s_add_i32 m0, s52, 0x2000
	s_nop 0
	global_load_lds_dwordx4 v130, s[24:25]
	s_waitcnt vmcnt(6)
	s_barrier
	v_mfma_f32_16x16x32_bf16 v[54:57], v[230:233], v[180:183], v[54:57]
	v_mfma_f32_16x16x32_bf16 v[46:49], v[238:241], v[180:183], v[46:49]
	v_mfma_f32_16x16x32_bf16 v[38:41], v[230:233], v[206:209], v[38:41]
	v_mfma_f32_16x16x32_bf16 v[30:33], v[238:241], v[206:209], v[30:33]
	v_mfma_f32_16x16x32_bf16 v[22:25], v[230:233], v[214:217], v[22:25]
	v_mfma_f32_16x16x32_bf16 v[14:17], v[238:241], v[214:217], v[14:17]
	v_mfma_f32_16x16x32_bf16 v[6:9], v[230:233], v[222:225], v[6:9]
	v_mfma_f32_16x16x32_bf16 v[2:5], v[238:241], v[222:225], v[2:5]
	v_mfma_f32_16x16x32_bf16 v[54:57], v[234:237], v[184:187], v[54:57]
	v_mfma_f32_16x16x32_bf16 v[46:49], v[242:245], v[184:187], v[46:49]
	v_mfma_f32_16x16x32_bf16 v[38:41], v[234:237], v[210:213], v[38:41]
	v_mfma_f32_16x16x32_bf16 v[30:33], v[242:245], v[210:213], v[30:33]
	v_mfma_f32_16x16x32_bf16 v[22:25], v[234:237], v[218:221], v[22:25]
	v_mfma_f32_16x16x32_bf16 v[14:17], v[242:245], v[218:221], v[14:17]
	v_mfma_f32_16x16x32_bf16 v[6:9], v[234:237], v[226:229], v[6:9]
	v_mfma_f32_16x16x32_bf16 v[2:5], v[242:245], v[226:229], v[2:5]
	s_barrier
	s_add_i32 s52, 0, 0x18000
	v_add_u32_e32 v163, s52, v144
	ds_read_b128 v[164:167], v163
	ds_read_b128 v[168:171], v163 offset:1024
	ds_read_b128 v[172:175], v163 offset:2048
	ds_read_b128 v[176:179], v163 offset:3072
	s_add_u32 s24, s28, 0xb0000
	s_addc_u32 s25, s29, 0
	s_mov_b32 m0, s37
	v_lshl_add_u64 v[230:231], s[24:25], 0, v[134:135]
	ds_read_b128 v[180:183], v162 offset:32768
	ds_read_b128 v[184:187], v162 offset:33792
	ds_read_b128 v[206:209], v162 offset:34816
	ds_read_b128 v[210:213], v162 offset:35840
	ds_read_b128 v[214:217], v162 offset:36864
	ds_read_b128 v[218:221], v162 offset:37888
	ds_read_b128 v[222:225], v162 offset:38912
	ds_read_b128 v[226:229], v162 offset:39936
	global_load_lds_dwordx4 v[230:231], off
	s_mov_b32 m0, s42
	s_nop 0
	global_load_lds_dwordx4 v132, s[24:25]
	s_waitcnt lgkmcnt(8)
	s_barrier
	s_waitcnt lgkmcnt(0)
	v_mfma_f32_16x16x32_bf16 v[126:129], v[164:167], v[180:183], v[126:129]
	v_mfma_f32_16x16x32_bf16 v[122:125], v[172:175], v[180:183], v[122:125]
	v_mfma_f32_16x16x32_bf16 v[114:117], v[164:167], v[206:209], v[114:117]
	v_mfma_f32_16x16x32_bf16 v[106:109], v[172:175], v[206:209], v[106:109]
	v_mfma_f32_16x16x32_bf16 v[98:101], v[164:167], v[214:217], v[98:101]
	v_mfma_f32_16x16x32_bf16 v[90:93], v[172:175], v[214:217], v[90:93]
	v_mfma_f32_16x16x32_bf16 v[82:85], v[164:167], v[222:225], v[82:85]
	v_mfma_f32_16x16x32_bf16 v[74:77], v[172:175], v[222:225], v[74:77]
	v_mfma_f32_16x16x32_bf16 v[126:129], v[168:171], v[184:187], v[126:129]
	v_mfma_f32_16x16x32_bf16 v[122:125], v[176:179], v[184:187], v[122:125]
	v_mfma_f32_16x16x32_bf16 v[114:117], v[168:171], v[210:213], v[114:117]
	v_mfma_f32_16x16x32_bf16 v[106:109], v[176:179], v[210:213], v[106:109]
	v_mfma_f32_16x16x32_bf16 v[98:101], v[168:171], v[218:221], v[98:101]
	v_mfma_f32_16x16x32_bf16 v[90:93], v[176:179], v[218:221], v[90:93]
	v_mfma_f32_16x16x32_bf16 v[82:85], v[168:171], v[226:229], v[82:85]
	v_mfma_f32_16x16x32_bf16 v[74:77], v[176:179], v[226:229], v[74:77]
	s_barrier
	s_add_i32 s28, 0, 0x1c000
	s_add_i32 s24, s52, s31
	v_add_u32_e32 v163, s28, v144
	v_lshl_add_u64 v[140:141], v[140:141], 0, s[94:95]
	s_mov_b32 m0, s24
	ds_read_b128 v[230:233], v163
	ds_read_b128 v[234:237], v163 offset:1024
	ds_read_b128 v[238:241], v163 offset:2048
	ds_read_b128 v[242:245], v163 offset:3072
	global_load_lds_dwordx4 v[140:141], off
	s_add_i32 m0, s24, 0x2000
	v_lshl_add_u64 v[140:141], v[246:247], 0, s[94:95]
	global_load_lds_dwordx4 v[140:141], off
	s_barrier
	s_waitcnt lgkmcnt(0)
	v_mfma_f32_16x16x32_bf16 v[118:121], v[230:233], v[180:183], v[118:121]
	v_mfma_f32_16x16x32_bf16 v[110:113], v[238:241], v[180:183], v[110:113]
	v_mfma_f32_16x16x32_bf16 v[102:105], v[230:233], v[206:209], v[102:105]
	v_mfma_f32_16x16x32_bf16 v[94:97], v[238:241], v[206:209], v[94:97]
	v_mfma_f32_16x16x32_bf16 v[86:89], v[230:233], v[214:217], v[86:89]
	v_mfma_f32_16x16x32_bf16 v[78:81], v[238:241], v[214:217], v[78:81]
	v_mfma_f32_16x16x32_bf16 v[70:73], v[230:233], v[222:225], v[70:73]
	v_mfma_f32_16x16x32_bf16 v[66:69], v[238:241], v[222:225], v[66:69]
	v_mfma_f32_16x16x32_bf16 v[118:121], v[234:237], v[184:187], v[118:121]
	v_mfma_f32_16x16x32_bf16 v[110:113], v[242:245], v[184:187], v[110:113]
	v_mfma_f32_16x16x32_bf16 v[102:105], v[234:237], v[210:213], v[102:105]
	v_mfma_f32_16x16x32_bf16 v[94:97], v[242:245], v[210:213], v[94:97]
	v_mfma_f32_16x16x32_bf16 v[86:89], v[234:237], v[218:221], v[86:89]
	v_mfma_f32_16x16x32_bf16 v[78:81], v[242:245], v[218:221], v[78:81]
	v_mfma_f32_16x16x32_bf16 v[70:73], v[234:237], v[226:229], v[70:73]
	v_mfma_f32_16x16x32_bf16 v[66:69], v[242:245], v[226:229], v[66:69]
	s_barrier
	s_mov_b32 m0, s44
	v_lshl_add_u64 v[140:141], v[248:249], 0, s[94:95]
	ds_read_b128 v[180:183], v162 offset:49152
	ds_read_b128 v[184:187], v162 offset:50176
	ds_read_b128 v[206:209], v162 offset:51200
	ds_read_b128 v[210:213], v162 offset:52224
	ds_read_b128 v[214:217], v162 offset:53248
	ds_read_b128 v[218:221], v162 offset:54272
	ds_read_b128 v[222:225], v162 offset:55296
	ds_read_b128 v[226:229], v162 offset:56320
	global_load_lds_dwordx4 v[140:141], off
	s_mov_b32 m0, s45
	v_lshl_add_u64 v[140:141], v[250:251], 0, s[94:95]
	global_load_lds_dwordx4 v[140:141], off
	s_barrier
	s_waitcnt lgkmcnt(0)
	v_mfma_f32_16x16x32_bf16 v[62:65], v[164:167], v[180:183], v[62:65]
	v_mfma_f32_16x16x32_bf16 v[58:61], v[172:175], v[180:183], v[58:61]
	v_mfma_f32_16x16x32_bf16 v[50:53], v[164:167], v[206:209], v[50:53]
	v_mfma_f32_16x16x32_bf16 v[42:45], v[172:175], v[206:209], v[42:45]
	v_mfma_f32_16x16x32_bf16 v[34:37], v[164:167], v[214:217], v[34:37]
	v_mfma_f32_16x16x32_bf16 v[26:29], v[172:175], v[214:217], v[26:29]
	v_mfma_f32_16x16x32_bf16 v[18:21], v[164:167], v[222:225], v[18:21]
	v_mfma_f32_16x16x32_bf16 v[10:13], v[172:175], v[222:225], v[10:13]
	v_mfma_f32_16x16x32_bf16 v[62:65], v[168:171], v[184:187], v[62:65]
	v_mfma_f32_16x16x32_bf16 v[58:61], v[176:179], v[184:187], v[58:61]
	v_mfma_f32_16x16x32_bf16 v[50:53], v[168:171], v[210:213], v[50:53]
	v_mfma_f32_16x16x32_bf16 v[42:45], v[176:179], v[210:213], v[42:45]
	v_mfma_f32_16x16x32_bf16 v[34:37], v[168:171], v[218:221], v[34:37]
	v_mfma_f32_16x16x32_bf16 v[26:29], v[176:179], v[218:221], v[26:29]
	v_mfma_f32_16x16x32_bf16 v[18:21], v[168:171], v[226:229], v[18:21]
	v_mfma_f32_16x16x32_bf16 v[10:13], v[176:179], v[226:229], v[10:13]
	s_barrier
	s_add_u32 s24, s26, 0xb0080
	s_addc_u32 s25, s27, 0
	s_add_i32 s26, s28, s31
	s_mov_b32 m0, s26
	s_nop 0
	global_load_lds_dwordx4 v0, s[24:25]
	s_add_i32 m0, s26, 0x2000
	s_nop 0
	global_load_lds_dwordx4 v130, s[24:25]
	s_waitcnt vmcnt(6)
	s_barrier
	v_mfma_f32_16x16x32_bf16 v[54:57], v[230:233], v[180:183], v[54:57]
	v_mfma_f32_16x16x32_bf16 v[46:49], v[238:241], v[180:183], v[46:49]
	v_mfma_f32_16x16x32_bf16 v[38:41], v[230:233], v[206:209], v[38:41]
	v_mfma_f32_16x16x32_bf16 v[30:33], v[238:241], v[206:209], v[30:33]
	v_mfma_f32_16x16x32_bf16 v[22:25], v[230:233], v[214:217], v[22:25]
	v_mfma_f32_16x16x32_bf16 v[14:17], v[238:241], v[214:217], v[14:17]
	v_mfma_f32_16x16x32_bf16 v[6:9], v[230:233], v[222:225], v[6:9]
	v_mfma_f32_16x16x32_bf16 v[2:5], v[238:241], v[222:225], v[2:5]
	v_mfma_f32_16x16x32_bf16 v[54:57], v[234:237], v[184:187], v[54:57]
	v_mfma_f32_16x16x32_bf16 v[46:49], v[242:245], v[184:187], v[46:49]
	v_mfma_f32_16x16x32_bf16 v[38:41], v[234:237], v[210:213], v[38:41]
	v_mfma_f32_16x16x32_bf16 v[30:33], v[242:245], v[210:213], v[30:33]
	v_mfma_f32_16x16x32_bf16 v[22:25], v[234:237], v[218:221], v[22:25]
	v_mfma_f32_16x16x32_bf16 v[14:17], v[242:245], v[218:221], v[14:17]
	v_mfma_f32_16x16x32_bf16 v[6:9], v[234:237], v[226:229], v[6:9]
	v_mfma_f32_16x16x32_bf16 v[2:5], v[242:245], v[226:229], v[2:5]
	s_barrier
	s_add_i32 s51, s51, 2
	s_add_u32 s40, s40, 0x100
	s_addc_u32 s41, s41, 0
	s_cmp_gt_u32 s51, 41
	s_mov_b64 s[24:25], s[22:23]
	s_cbranch_scc0 .LBB0_331
	v_lshl_or_b32 v140, s50, 8, v145
	v_lshl_add_u32 v164, s49, 8, v143
	v_ashrrev_i32_e32 v141, 31, v140
	v_ashrrev_i32_e32 v165, 31, v164
	v_lshl_add_u64 v[166:167], v[140:141], 1, s[20:21]
	v_lshlrev_b64 v[140:141], 11, v[164:165]
	v_lshl_add_u64 v[140:141], v[166:167], 0, v[140:141]
	v_pk_add_f32 v[128:129], v[128:129], 0 op_sel_hi:[1,0]
	v_pk_add_f32 v[126:127], v[126:127], 0 op_sel_hi:[1,0]
	v_pk_add_f32 v[168:169], v[124:125], 0 op_sel_hi:[1,0]
	v_pk_add_f32 v[124:125], v[122:123], 0 op_sel_hi:[1,0]
	v_cvt_pk_bf16_f32 v122, v126, v127
	v_cvt_pk_bf16_f32 v123, v128, v129
	v_pk_add_f32 v[118:119], v[118:119], 0 op_sel_hi:[1,0]
	v_cvt_pk_bf16_f32 v124, v124, v125
	v_cvt_pk_bf16_f32 v125, v168, v169
	global_store_dwordx4 v[140:141], v[122:125], off
	v_pk_add_f32 v[120:121], v[120:121], 0 op_sel_hi:[1,0]
	v_pk_add_f32 v[114:115], v[114:115], 0 op_sel_hi:[1,0]
	v_pk_add_f32 v[122:123], v[112:113], 0 op_sel_hi:[1,0]
	v_pk_add_f32 v[112:113], v[110:111], 0 op_sel_hi:[1,0]
	v_cvt_pk_bf16_f32 v110, v118, v119
	v_cvt_pk_bf16_f32 v111, v120, v121
	v_pk_add_f32 v[102:103], v[102:103], 0 op_sel_hi:[1,0]
	v_cvt_pk_bf16_f32 v112, v112, v113
	v_cvt_pk_bf16_f32 v113, v122, v123
	global_store_dwordx4 v[140:141], v[110:113], off offset:256
	v_pk_add_f32 v[104:105], v[104:105], 0 op_sel_hi:[1,0]
	v_pk_add_f32 v[98:99], v[98:99], 0 op_sel_hi:[1,0]
	v_or_b32_e32 v110, 16, v164
	v_ashrrev_i32_e32 v111, 31, v110
	v_lshlrev_b64 v[110:111], 11, v[110:111]
	v_lshl_add_u64 v[110:111], v[166:167], 0, v[110:111]
	v_pk_add_f32 v[112:113], v[116:117], 0 op_sel_hi:[1,0]
	v_pk_add_f32 v[116:117], v[108:109], 0 op_sel_hi:[1,0]
	v_pk_add_f32 v[108:109], v[106:107], 0 op_sel_hi:[1,0]
	v_cvt_pk_bf16_f32 v106, v114, v115
	v_cvt_pk_bf16_f32 v107, v112, v113
	v_pk_add_f32 v[86:87], v[86:87], 0 op_sel_hi:[1,0]
	v_cvt_pk_bf16_f32 v108, v108, v109
	v_cvt_pk_bf16_f32 v109, v116, v117
	global_store_dwordx4 v[110:111], v[106:109], off
	v_pk_add_f32 v[88:89], v[88:89], 0 op_sel_hi:[1,0]
	v_pk_add_f32 v[82:83], v[82:83], 0 op_sel_hi:[1,0]
	v_pk_add_f32 v[106:107], v[96:97], 0 op_sel_hi:[1,0]
	v_pk_add_f32 v[96:97], v[94:95], 0 op_sel_hi:[1,0]
	v_cvt_pk_bf16_f32 v94, v102, v103
	v_cvt_pk_bf16_f32 v95, v104, v105
	v_pk_add_f32 v[72:73], v[72:73], 0 op_sel_hi:[1,0]
	v_cvt_pk_bf16_f32 v96, v96, v97
	v_cvt_pk_bf16_f32 v97, v106, v107
	global_store_dwordx4 v[110:111], v[94:97], off offset:256
	v_pk_add_f32 v[70:71], v[70:71], 0 op_sel_hi:[1,0]
	v_pk_add_f32 v[62:63], v[62:63], 0 op_sel_hi:[1,0]
	v_or_b32_e32 v94, 32, v164
	v_ashrrev_i32_e32 v95, 31, v94
	v_lshlrev_b64 v[94:95], 11, v[94:95]
	v_lshl_add_u64 v[94:95], v[166:167], 0, v[94:95]
	v_pk_add_f32 v[96:97], v[100:101], 0 op_sel_hi:[1,0]
	v_pk_add_f32 v[100:101], v[92:93], 0 op_sel_hi:[1,0]
	v_pk_add_f32 v[92:93], v[90:91], 0 op_sel_hi:[1,0]
	v_cvt_pk_bf16_f32 v90, v98, v99
	v_cvt_pk_bf16_f32 v91, v96, v97
	v_pk_add_f32 v[64:65], v[64:65], 0 op_sel_hi:[1,0]
	v_cvt_pk_bf16_f32 v92, v92, v93
	v_cvt_pk_bf16_f32 v93, v100, v101
	global_store_dwordx4 v[94:95], v[90:93], off
	s_mov_b64 s[22:23], 0x40000
	v_pk_add_f32 v[56:57], v[56:57], 0 op_sel_hi:[1,0]
	v_pk_add_f32 v[90:91], v[80:81], 0 op_sel_hi:[1,0]
	v_pk_add_f32 v[80:81], v[78:79], 0 op_sel_hi:[1,0]
	v_cvt_pk_bf16_f32 v78, v86, v87
	v_cvt_pk_bf16_f32 v79, v88, v89
	v_pk_add_f32 v[54:55], v[54:55], 0 op_sel_hi:[1,0]
	v_cvt_pk_bf16_f32 v80, v80, v81
	v_cvt_pk_bf16_f32 v81, v90, v91
	global_store_dwordx4 v[94:95], v[78:81], off offset:256
	v_pk_add_f32 v[50:51], v[50:51], 0 op_sel_hi:[1,0]
	v_pk_add_f32 v[40:41], v[40:41], 0 op_sel_hi:[1,0]
	v_or_b32_e32 v78, 48, v164
	v_ashrrev_i32_e32 v79, 31, v78
	v_lshlrev_b64 v[78:79], 11, v[78:79]
	v_lshl_add_u64 v[78:79], v[166:167], 0, v[78:79]
	v_pk_add_f32 v[80:81], v[84:85], 0 op_sel_hi:[1,0]
	v_pk_add_f32 v[84:85], v[76:77], 0 op_sel_hi:[1,0]
	v_pk_add_f32 v[76:77], v[74:75], 0 op_sel_hi:[1,0]
	v_cvt_pk_bf16_f32 v74, v82, v83
	v_cvt_pk_bf16_f32 v75, v80, v81
	v_pk_add_f32 v[38:39], v[38:39], 0 op_sel_hi:[1,0]
	v_cvt_pk_bf16_f32 v76, v76, v77
	v_cvt_pk_bf16_f32 v77, v84, v85
	global_store_dwordx4 v[78:79], v[74:77], off
	v_pk_add_f32 v[34:35], v[34:35], 0 op_sel_hi:[1,0]
	v_pk_add_f32 v[24:25], v[24:25], 0 op_sel_hi:[1,0]
	v_pk_add_f32 v[74:75], v[68:69], 0 op_sel_hi:[1,0]
	v_pk_add_f32 v[68:69], v[66:67], 0 op_sel_hi:[1,0]
	v_cvt_pk_bf16_f32 v66, v70, v71
	v_cvt_pk_bf16_f32 v67, v72, v73
	v_pk_add_f32 v[22:23], v[22:23], 0 op_sel_hi:[1,0]
	v_cvt_pk_bf16_f32 v68, v68, v69
	v_cvt_pk_bf16_f32 v69, v74, v75
	global_store_dwordx4 v[78:79], v[66:69], off offset:256
	v_pk_add_f32 v[18:19], v[18:19], 0 op_sel_hi:[1,0]
	s_mov_b32 s50, s47
	v_pk_add_f32 v[68:69], v[60:61], 0 op_sel_hi:[1,0]
	v_pk_add_f32 v[60:61], v[58:59], 0 op_sel_hi:[1,0]
	v_cvt_pk_bf16_f32 v58, v62, v63
	v_add_co_u32_e32 v62, vcc, s67, v140
	v_cvt_pk_bf16_f32 v59, v64, v65
	v_cvt_pk_bf16_f32 v60, v60, v61
	v_cvt_pk_bf16_f32 v61, v68, v69
	v_lshl_add_u64 v[66:67], v[140:141], 0, s[22:23]
	s_nop 0
	v_addc_co_u32_e32 v63, vcc, 0, v141, vcc
	global_store_dwordx4 v[62:63], v[58:61], off
	s_mov_b64 s[22:23], 0x48000
	s_mov_b32 s49, s48
	v_pk_add_f32 v[58:59], v[48:49], 0 op_sel_hi:[1,0]
	v_pk_add_f32 v[48:49], v[46:47], 0 op_sel_hi:[1,0]
	v_cvt_pk_bf16_f32 v46, v54, v55
	v_cvt_pk_bf16_f32 v47, v56, v57
	s_mov_b64 s[24:25], s[2:3]
	v_cvt_pk_bf16_f32 v48, v48, v49
	v_cvt_pk_bf16_f32 v49, v58, v59
	global_store_dwordx4 v[66:67], v[46:49], off offset:256
	v_pk_add_f32 v[8:9], v[8:9], 0 op_sel_hi:[1,0]
	v_pk_add_f32 v[6:7], v[6:7], 0 op_sel_hi:[1,0]
	v_pk_add_f32 v[48:49], v[52:53], 0 op_sel_hi:[1,0]
	v_pk_add_f32 v[52:53], v[44:45], 0 op_sel_hi:[1,0]
	v_pk_add_f32 v[44:45], v[42:43], 0 op_sel_hi:[1,0]
	v_cvt_pk_bf16_f32 v42, v50, v51
	v_cvt_pk_bf16_f32 v43, v48, v49
	v_add_co_u32_e32 v48, vcc, s68, v140
	v_cvt_pk_bf16_f32 v44, v44, v45
	v_cvt_pk_bf16_f32 v45, v52, v53
	v_lshl_add_u64 v[46:47], v[140:141], 0, s[22:23]
	s_nop 0
	v_addc_co_u32_e32 v49, vcc, 0, v141, vcc
	global_store_dwordx4 v[48:49], v[42:45], off
	s_mov_b64 s[22:23], 0x50000
	s_nop 0
	v_pk_add_f32 v[42:43], v[32:33], 0 op_sel_hi:[1,0]
	v_pk_add_f32 v[32:33], v[30:31], 0 op_sel_hi:[1,0]
	v_cvt_pk_bf16_f32 v30, v38, v39
	v_cvt_pk_bf16_f32 v31, v40, v41
	s_nop 0
	v_cvt_pk_bf16_f32 v32, v32, v33
	v_cvt_pk_bf16_f32 v33, v42, v43
	global_store_dwordx4 v[46:47], v[30:33], off offset:256
	s_nop 1
	v_lshl_add_u64 v[30:31], v[140:141], 0, s[22:23]
	v_pk_add_f32 v[32:33], v[36:37], 0 op_sel_hi:[1,0]
	s_mov_b32 s22, 0x50000
	v_pk_add_f32 v[36:37], v[28:29], 0 op_sel_hi:[1,0]
	v_pk_add_f32 v[28:29], v[26:27], 0 op_sel_hi:[1,0]
	v_cvt_pk_bf16_f32 v26, v34, v35
	v_cvt_pk_bf16_f32 v27, v32, v33
	v_add_co_u32_e32 v32, vcc, s22, v140
	v_cvt_pk_bf16_f32 v28, v28, v29
	v_cvt_pk_bf16_f32 v29, v36, v37
	s_mov_b64 s[22:23], 0x58000
	s_nop 0
	v_addc_co_u32_e32 v33, vcc, 0, v141, vcc
	global_store_dwordx4 v[32:33], v[26:29], off
	s_nop 1
	v_pk_add_f32 v[26:27], v[16:17], 0 op_sel_hi:[1,0]
	v_pk_add_f32 v[16:17], v[14:15], 0 op_sel_hi:[1,0]
	v_cvt_pk_bf16_f32 v14, v22, v23
	v_cvt_pk_bf16_f32 v15, v24, v25
	s_nop 0
	v_cvt_pk_bf16_f32 v16, v16, v17
	v_cvt_pk_bf16_f32 v17, v26, v27
	global_store_dwordx4 v[30:31], v[14:17], off offset:256
	s_nop 1
	v_lshl_add_u64 v[14:15], v[140:141], 0, s[22:23]
	v_pk_add_f32 v[16:17], v[20:21], 0 op_sel_hi:[1,0]
	s_mov_b32 s22, 0x58000
	v_pk_add_f32 v[20:21], v[12:13], 0 op_sel_hi:[1,0]
	v_pk_add_f32 v[12:13], v[10:11], 0 op_sel_hi:[1,0]
	v_cvt_pk_bf16_f32 v10, v18, v19
	v_cvt_pk_bf16_f32 v11, v16, v17
	v_add_co_u32_e32 v16, vcc, s22, v140
	v_cvt_pk_bf16_f32 v12, v12, v13
	v_cvt_pk_bf16_f32 v13, v20, v21
	s_mov_b64 s[22:23], s[0:1]
	s_nop 0
	v_addc_co_u32_e32 v17, vcc, 0, v141, vcc
	global_store_dwordx4 v[16:17], v[10:13], off
	s_and_b64 vcc, exec, s[38:39]
	s_nop 0
	v_pk_add_f32 v[10:11], v[4:5], 0 op_sel_hi:[1,0]
	v_pk_add_f32 v[4:5], v[2:3], 0 op_sel_hi:[1,0]
	v_cvt_pk_bf16_f32 v2, v6, v7
	v_cvt_pk_bf16_f32 v3, v8, v9
	s_nop 0
	v_cvt_pk_bf16_f32 v4, v4, v5
	v_cvt_pk_bf16_f32 v5, v10, v11
	global_store_dwordx4 v[14:15], v[2:5], off offset:256
	s_cbranch_vccz .LBB0_320
	s_waitcnt vmcnt(16)
	s_cmpk_gt_u32 s30, 0xff
	s_cbranch_scc1 .LBB0_335
	s_barrier

.Lkprio_1:
.LBB0_360:
	s_add_u32 s44, s42, 0xfffc0080
	s_addc_u32 s45, s43, -1
	s_add_i32 s63, 0, 0x10000
	v_add_u32_e32 v0, s63, v206
	ds_read_b128 v[82:85], v0
	ds_read_b128 v[86:89], v0 offset:1024
	ds_read_b128 v[90:93], v0 offset:2048
	ds_read_b128 v[94:97], v0 offset:3072
	s_cmp_eq_u32 s62, 12
	s_cselect_b32 s47, s1, s45
	s_cselect_b32 s46, s3, s44
	s_cselect_b32 s45, s31, s61
	s_cselect_b32 s44, s35, s60
	v_lshl_add_u64 v[230:231], s[42:43], 0, v[174:175]
	s_add_i32 m0, s51, 0xc000
	ds_read_b128 v[176:179], v208
	ds_read_b128 v[180:183], v208 offset:1024
	ds_read_b128 v[184:187], v208 offset:2048
	ds_read_b128 v[210:213], v208 offset:3072
	ds_read_b128 v[214:217], v208 offset:4096
	ds_read_b128 v[218:221], v208 offset:5120
	ds_read_b128 v[222:225], v208 offset:6144
	ds_read_b128 v[226:229], v208 offset:7168
	global_load_lds_dwordx4 v[230:231], off
	s_add_i32 m0, s51, 0xe000
	s_nop 0
	global_load_lds_dwordx4 v172, s[42:43]
	s_waitcnt lgkmcnt(8)
	s_barrier
	s_waitcnt lgkmcnt(0)
	v_mfma_f32_16x16x32_bf16 v[142:145], v[82:85], v[176:179], v[142:145]
	v_mfma_f32_16x16x32_bf16 v[138:141], v[90:93], v[176:179], v[138:141]
	v_mfma_f32_16x16x32_bf16 v[126:129], v[82:85], v[184:187], v[126:129]
	v_mfma_f32_16x16x32_bf16 v[122:125], v[90:93], v[184:187], v[122:125]
	v_mfma_f32_16x16x32_bf16 v[110:113], v[82:85], v[214:217], v[110:113]
	v_mfma_f32_16x16x32_bf16 v[106:109], v[90:93], v[214:217], v[106:109]
	v_mfma_f32_16x16x32_bf16 v[78:81], v[82:85], v[222:225], v[78:81]
	v_mfma_f32_16x16x32_bf16 v[74:77], v[90:93], v[222:225], v[74:77]
	v_mfma_f32_16x16x32_bf16 v[142:145], v[86:89], v[180:183], v[142:145]
	v_mfma_f32_16x16x32_bf16 v[138:141], v[94:97], v[180:183], v[138:141]
	v_mfma_f32_16x16x32_bf16 v[126:129], v[86:89], v[210:213], v[126:129]
	v_mfma_f32_16x16x32_bf16 v[122:125], v[94:97], v[210:213], v[122:125]
	v_mfma_f32_16x16x32_bf16 v[110:113], v[86:89], v[218:221], v[110:113]
	v_mfma_f32_16x16x32_bf16 v[106:109], v[94:97], v[218:221], v[106:109]
	v_mfma_f32_16x16x32_bf16 v[78:81], v[86:89], v[226:229], v[78:81]
	v_mfma_f32_16x16x32_bf16 v[74:77], v[94:97], v[226:229], v[74:77]
	s_barrier
	s_add_i32 s66, 0, 0x14000
	s_add_i32 s63, s63, s50
	v_add_u32_e32 v0, s66, v206
	v_lshl_add_u64 v[246:247], s[44:45], 0, v[164:165]
	s_mov_b32 m0, s63
	ds_read_b128 v[230:233], v0
	ds_read_b128 v[234:237], v0 offset:1024
	ds_read_b128 v[238:241], v0 offset:2048
	ds_read_b128 v[242:245], v0 offset:3072
	global_load_lds_dwordx4 v[246:247], off
	s_add_i32 m0, s63, 0x2000
	v_lshl_add_u64 v[248:249], s[44:45], 0, v[168:169]
	global_load_lds_dwordx4 v[248:249], off
	s_barrier
	s_waitcnt lgkmcnt(0)
	v_mfma_f32_16x16x32_bf16 v[134:137], v[230:233], v[176:179], v[134:137]
	v_mfma_f32_16x16x32_bf16 v[130:133], v[238:241], v[176:179], v[130:133]
	v_mfma_f32_16x16x32_bf16 v[118:121], v[230:233], v[184:187], v[118:121]
	v_mfma_f32_16x16x32_bf16 v[114:117], v[238:241], v[184:187], v[114:117]
	v_mfma_f32_16x16x32_bf16 v[102:105], v[230:233], v[214:217], v[102:105]
	v_mfma_f32_16x16x32_bf16 v[98:101], v[238:241], v[214:217], v[98:101]
	v_mfma_f32_16x16x32_bf16 v[70:73], v[230:233], v[222:225], v[70:73]
	v_mfma_f32_16x16x32_bf16 v[66:69], v[238:241], v[222:225], v[66:69]
	v_mfma_f32_16x16x32_bf16 v[134:137], v[234:237], v[180:183], v[134:137]
	v_mfma_f32_16x16x32_bf16 v[130:133], v[242:245], v[180:183], v[130:133]
	v_mfma_f32_16x16x32_bf16 v[118:121], v[234:237], v[210:213], v[118:121]
	v_mfma_f32_16x16x32_bf16 v[114:117], v[242:245], v[210:213], v[114:117]
	v_mfma_f32_16x16x32_bf16 v[102:105], v[234:237], v[218:221], v[102:105]
	v_mfma_f32_16x16x32_bf16 v[98:101], v[242:245], v[218:221], v[98:101]
	v_mfma_f32_16x16x32_bf16 v[70:73], v[234:237], v[226:229], v[70:73]
	v_mfma_f32_16x16x32_bf16 v[66:69], v[242:245], v[226:229], v[66:69]
	s_barrier
	s_mov_b32 m0, s51
	v_lshl_add_u64 v[250:251], s[46:47], 0, v[162:163]
	ds_read_b128 v[176:179], v208 offset:16384
	ds_read_b128 v[180:183], v208 offset:17408
	ds_read_b128 v[184:187], v208 offset:18432
	ds_read_b128 v[210:213], v208 offset:19456
	ds_read_b128 v[214:217], v208 offset:20480
	ds_read_b128 v[218:221], v208 offset:21504
	ds_read_b128 v[222:225], v208 offset:22528
	ds_read_b128 v[226:229], v208 offset:23552
	global_load_lds_dwordx4 v[250:251], off
	s_mov_b32 m0, s52
	v_lshl_add_u64 v[252:253], s[46:47], 0, v[166:167]
	global_load_lds_dwordx4 v[252:253], off
	s_barrier
	s_waitcnt lgkmcnt(0)
	v_mfma_f32_16x16x32_bf16 v[62:65], v[82:85], v[176:179], v[62:65]
	v_mfma_f32_16x16x32_bf16 v[58:61], v[90:93], v[176:179], v[58:61]
	v_mfma_f32_16x16x32_bf16 v[46:49], v[82:85], v[184:187], v[46:49]
	v_mfma_f32_16x16x32_bf16 v[42:45], v[90:93], v[184:187], v[42:45]
	v_mfma_f32_16x16x32_bf16 v[30:33], v[82:85], v[214:217], v[30:33]
	v_mfma_f32_16x16x32_bf16 v[26:29], v[90:93], v[214:217], v[26:29]
	v_mfma_f32_16x16x32_bf16 v[14:17], v[82:85], v[222:225], v[14:17]
	v_mfma_f32_16x16x32_bf16 v[10:13], v[90:93], v[222:225], v[10:13]
	v_mfma_f32_16x16x32_bf16 v[62:65], v[86:89], v[180:183], v[62:65]
	v_mfma_f32_16x16x32_bf16 v[58:61], v[94:97], v[180:183], v[58:61]
	v_mfma_f32_16x16x32_bf16 v[46:49], v[86:89], v[210:213], v[46:49]
	v_mfma_f32_16x16x32_bf16 v[42:45], v[94:97], v[210:213], v[42:45]
	v_mfma_f32_16x16x32_bf16 v[30:33], v[86:89], v[218:221], v[30:33]
	v_mfma_f32_16x16x32_bf16 v[26:29], v[94:97], v[218:221], v[26:29]
	v_mfma_f32_16x16x32_bf16 v[14:17], v[86:89], v[226:229], v[14:17]
	v_mfma_f32_16x16x32_bf16 v[10:13], v[94:97], v[226:229], v[10:13]
	s_barrier
	s_add_u32 s64, s44, 0x40000
	s_addc_u32 s65, s45, 0
	s_add_i32 s63, s66, s50
	s_mov_b32 m0, s63
	s_nop 0
	global_load_lds_dwordx4 v164, s[64:65]
	s_add_i32 m0, s63, 0x2000
	s_nop 0
	global_load_lds_dwordx4 v168, s[64:65]
	s_waitcnt vmcnt(6)
	s_barrier
	v_mfma_f32_16x16x32_bf16 v[54:57], v[230:233], v[176:179], v[54:57]
	v_mfma_f32_16x16x32_bf16 v[50:53], v[238:241], v[176:179], v[50:53]
	v_mfma_f32_16x16x32_bf16 v[38:41], v[230:233], v[184:187], v[38:41]
	v_mfma_f32_16x16x32_bf16 v[34:37], v[238:241], v[184:187], v[34:37]
	v_mfma_f32_16x16x32_bf16 v[22:25], v[230:233], v[214:217], v[22:25]
	v_mfma_f32_16x16x32_bf16 v[18:21], v[238:241], v[214:217], v[18:21]
	v_mfma_f32_16x16x32_bf16 v[6:9], v[230:233], v[222:225], v[6:9]
	v_mfma_f32_16x16x32_bf16 v[2:5], v[238:241], v[222:225], v[2:5]
	v_mfma_f32_16x16x32_bf16 v[54:57], v[234:237], v[180:183], v[54:57]
	v_mfma_f32_16x16x32_bf16 v[50:53], v[242:245], v[180:183], v[50:53]
	v_mfma_f32_16x16x32_bf16 v[38:41], v[234:237], v[210:213], v[38:41]
	v_mfma_f32_16x16x32_bf16 v[34:37], v[242:245], v[210:213], v[34:37]
	v_mfma_f32_16x16x32_bf16 v[22:25], v[234:237], v[218:221], v[22:25]
	v_mfma_f32_16x16x32_bf16 v[18:21], v[242:245], v[218:221], v[18:21]
	v_mfma_f32_16x16x32_bf16 v[6:9], v[234:237], v[226:229], v[6:9]
	v_mfma_f32_16x16x32_bf16 v[2:5], v[242:245], v[226:229], v[2:5]
	s_barrier
	s_add_i32 s63, 0, 0x18000
	v_add_u32_e32 v0, s63, v206
	ds_read_b128 v[82:85], v0
	ds_read_b128 v[86:89], v0 offset:1024
	ds_read_b128 v[90:93], v0 offset:2048
	ds_read_b128 v[94:97], v0 offset:3072
	s_add_u32 s46, s46, 0x40000
	s_addc_u32 s47, s47, 0
	s_mov_b32 m0, s53
	v_lshl_add_u64 v[230:231], s[46:47], 0, v[162:163]
	ds_read_b128 v[176:179], v208 offset:32768
	ds_read_b128 v[180:183], v208 offset:33792
	ds_read_b128 v[184:187], v208 offset:34816
	ds_read_b128 v[210:213], v208 offset:35840
	ds_read_b128 v[214:217], v208 offset:36864
	ds_read_b128 v[218:221], v208 offset:37888
	ds_read_b128 v[222:225], v208 offset:38912
	ds_read_b128 v[226:229], v208 offset:39936
	global_load_lds_dwordx4 v[230:231], off
	s_mov_b32 m0, s54
	s_nop 0
	global_load_lds_dwordx4 v166, s[46:47]
	s_waitcnt lgkmcnt(8)
	s_barrier
	s_waitcnt lgkmcnt(0)
	v_mfma_f32_16x16x32_bf16 v[142:145], v[82:85], v[176:179], v[142:145]
	v_mfma_f32_16x16x32_bf16 v[138:141], v[90:93], v[176:179], v[138:141]
	v_mfma_f32_16x16x32_bf16 v[126:129], v[82:85], v[184:187], v[126:129]
	v_mfma_f32_16x16x32_bf16 v[122:125], v[90:93], v[184:187], v[122:125]
	v_mfma_f32_16x16x32_bf16 v[110:113], v[82:85], v[214:217], v[110:113]
	v_mfma_f32_16x16x32_bf16 v[106:109], v[90:93], v[214:217], v[106:109]
	v_mfma_f32_16x16x32_bf16 v[78:81], v[82:85], v[222:225], v[78:81]
	v_mfma_f32_16x16x32_bf16 v[74:77], v[90:93], v[222:225], v[74:77]
	v_mfma_f32_16x16x32_bf16 v[142:145], v[86:89], v[180:183], v[142:145]
	v_mfma_f32_16x16x32_bf16 v[138:141], v[94:97], v[180:183], v[138:141]
	v_mfma_f32_16x16x32_bf16 v[126:129], v[86:89], v[210:213], v[126:129]
	v_mfma_f32_16x16x32_bf16 v[122:125], v[94:97], v[210:213], v[122:125]
	v_mfma_f32_16x16x32_bf16 v[110:113], v[86:89], v[218:221], v[110:113]
	v_mfma_f32_16x16x32_bf16 v[106:109], v[94:97], v[218:221], v[106:109]
	v_mfma_f32_16x16x32_bf16 v[78:81], v[86:89], v[226:229], v[78:81]
	v_mfma_f32_16x16x32_bf16 v[74:77], v[94:97], v[226:229], v[74:77]
	s_barrier
	s_add_i32 s46, 0, 0x1c000
	s_add_i32 s47, s63, s50
	v_add_u32_e32 v0, s46, v206
	v_lshl_add_u64 v[246:247], v[246:247], 0, s[94:95]
	s_mov_b32 m0, s47
	ds_read_b128 v[230:233], v0
	ds_read_b128 v[234:237], v0 offset:1024
	ds_read_b128 v[238:241], v0 offset:2048
	ds_read_b128 v[242:245], v0 offset:3072
	global_load_lds_dwordx4 v[246:247], off
	s_add_i32 m0, s47, 0x2000
	v_lshl_add_u64 v[246:247], v[248:249], 0, s[94:95]
	global_load_lds_dwordx4 v[246:247], off
	s_barrier
	s_waitcnt lgkmcnt(0)
	v_mfma_f32_16x16x32_bf16 v[134:137], v[230:233], v[176:179], v[134:137]
	v_mfma_f32_16x16x32_bf16 v[130:133], v[238:241], v[176:179], v[130:133]
	v_mfma_f32_16x16x32_bf16 v[118:121], v[230:233], v[184:187], v[118:121]
	v_mfma_f32_16x16x32_bf16 v[114:117], v[238:241], v[184:187], v[114:117]
	v_mfma_f32_16x16x32_bf16 v[102:105], v[230:233], v[214:217], v[102:105]
	v_mfma_f32_16x16x32_bf16 v[98:101], v[238:241], v[214:217], v[98:101]
	v_mfma_f32_16x16x32_bf16 v[70:73], v[230:233], v[222:225], v[70:73]
	v_mfma_f32_16x16x32_bf16 v[66:69], v[238:241], v[222:225], v[66:69]
	v_mfma_f32_16x16x32_bf16 v[134:137], v[234:237], v[180:183], v[134:137]
	v_mfma_f32_16x16x32_bf16 v[130:133], v[242:245], v[180:183], v[130:133]
	v_mfma_f32_16x16x32_bf16 v[118:121], v[234:237], v[210:213], v[118:121]
	v_mfma_f32_16x16x32_bf16 v[114:117], v[242:245], v[210:213], v[114:117]
	v_mfma_f32_16x16x32_bf16 v[102:105], v[234:237], v[218:221], v[102:105]
	v_mfma_f32_16x16x32_bf16 v[98:101], v[242:245], v[218:221], v[98:101]
	v_mfma_f32_16x16x32_bf16 v[70:73], v[234:237], v[226:229], v[70:73]
	v_mfma_f32_16x16x32_bf16 v[66:69], v[242:245], v[226:229], v[66:69]
	s_barrier
	s_mov_b32 m0, s56
	v_lshl_add_u64 v[246:247], v[250:251], 0, s[94:95]
	ds_read_b128 v[176:179], v208 offset:49152
	ds_read_b128 v[180:183], v208 offset:50176
	ds_read_b128 v[184:187], v208 offset:51200
	ds_read_b128 v[210:213], v208 offset:52224
	ds_read_b128 v[214:217], v208 offset:53248
	ds_read_b128 v[218:221], v208 offset:54272
	ds_read_b128 v[222:225], v208 offset:55296
	ds_read_b128 v[226:229], v208 offset:56320
	global_load_lds_dwordx4 v[246:247], off
	s_mov_b32 m0, s57
	v_lshl_add_u64 v[246:247], v[252:253], 0, s[94:95]
	global_load_lds_dwordx4 v[246:247], off
	s_barrier
	s_waitcnt lgkmcnt(0)
	v_mfma_f32_16x16x32_bf16 v[62:65], v[82:85], v[176:179], v[62:65]
	v_mfma_f32_16x16x32_bf16 v[58:61], v[90:93], v[176:179], v[58:61]
	v_mfma_f32_16x16x32_bf16 v[46:49], v[82:85], v[184:187], v[46:49]
	v_mfma_f32_16x16x32_bf16 v[42:45], v[90:93], v[184:187], v[42:45]
	v_mfma_f32_16x16x32_bf16 v[30:33], v[82:85], v[214:217], v[30:33]
	v_mfma_f32_16x16x32_bf16 v[26:29], v[90:93], v[214:217], v[26:29]
	v_mfma_f32_16x16x32_bf16 v[14:17], v[82:85], v[222:225], v[14:17]
	v_mfma_f32_16x16x32_bf16 v[10:13], v[90:93], v[222:225], v[10:13]
	v_mfma_f32_16x16x32_bf16 v[62:65], v[86:89], v[180:183], v[62:65]
	v_mfma_f32_16x16x32_bf16 v[58:61], v[94:97], v[180:183], v[58:61]
	v_mfma_f32_16x16x32_bf16 v[46:49], v[86:89], v[210:213], v[46:49]
	v_mfma_f32_16x16x32_bf16 v[42:45], v[94:97], v[210:213], v[42:45]
	v_mfma_f32_16x16x32_bf16 v[30:33], v[86:89], v[218:221], v[30:33]
	v_mfma_f32_16x16x32_bf16 v[26:29], v[94:97], v[218:221], v[26:29]
	v_mfma_f32_16x16x32_bf16 v[14:17], v[86:89], v[226:229], v[14:17]
	v_mfma_f32_16x16x32_bf16 v[10:13], v[94:97], v[226:229], v[10:13]
	s_barrier
	s_add_u32 s44, s44, 0x40080
	s_addc_u32 s45, s45, 0
	s_add_i32 s46, s46, s50
	s_mov_b32 m0, s46
	s_nop 0
	global_load_lds_dwordx4 v164, s[44:45]
	s_add_i32 m0, s46, 0x2000
	s_nop 0
	global_load_lds_dwordx4 v168, s[44:45]
	s_waitcnt vmcnt(6)
	s_barrier
	v_mfma_f32_16x16x32_bf16 v[54:57], v[230:233], v[176:179], v[54:57]
	v_mfma_f32_16x16x32_bf16 v[50:53], v[238:241], v[176:179], v[50:53]
	v_mfma_f32_16x16x32_bf16 v[38:41], v[230:233], v[184:187], v[38:41]
	v_mfma_f32_16x16x32_bf16 v[34:37], v[238:241], v[184:187], v[34:37]
	v_mfma_f32_16x16x32_bf16 v[22:25], v[230:233], v[214:217], v[22:25]
	v_mfma_f32_16x16x32_bf16 v[18:21], v[238:241], v[214:217], v[18:21]
	v_mfma_f32_16x16x32_bf16 v[6:9], v[230:233], v[222:225], v[6:9]
	v_mfma_f32_16x16x32_bf16 v[2:5], v[238:241], v[222:225], v[2:5]
	v_mfma_f32_16x16x32_bf16 v[54:57], v[234:237], v[180:183], v[54:57]
	v_mfma_f32_16x16x32_bf16 v[50:53], v[242:245], v[180:183], v[50:53]
	v_mfma_f32_16x16x32_bf16 v[38:41], v[234:237], v[210:213], v[38:41]
	v_mfma_f32_16x16x32_bf16 v[34:37], v[242:245], v[210:213], v[34:37]
	v_mfma_f32_16x16x32_bf16 v[22:25], v[234:237], v[218:221], v[22:25]
	v_mfma_f32_16x16x32_bf16 v[18:21], v[242:245], v[218:221], v[18:21]
	v_mfma_f32_16x16x32_bf16 v[6:9], v[234:237], v[226:229], v[6:9]
	v_mfma_f32_16x16x32_bf16 v[2:5], v[242:245], v[226:229], v[2:5]
	s_barrier
	s_add_i32 s62, s62, 2
	s_add_u32 s60, s60, 0x100
	s_addc_u32 s61, s61, 0
	s_add_u32 s42, s42, 0x100
	s_addc_u32 s43, s43, 0
	s_cmp_gt_u32 s62, 13
	s_cbranch_scc0 .LBB0_360
	v_lshl_or_b32 v180, s0, 8, v207
	v_ashrrev_i32_e32 v181, 31, v180
	v_mov_b32_e32 v86, 0
	v_cndmask_b32_e64 v0, 0, 1, s[26:27]
	v_lshl_add_u64 v[176:177], v[180:181], 2, s[22:23]
	v_cmp_ne_u32_e64 s[0:1], 1, v0
	s_andn2_b64 vcc, exec, s[26:27]
	v_mov_b32_e32 v94, 0
	v_mov_b32_e32 v95, v86
	v_mov_b32_e32 v96, 0
	v_mov_b32_e32 v97, 0
	s_cbranch_vccnz .LBB0_363
	global_load_dwordx4 v[94:97], v[176:177], off

.Lkprio_0:
.LBB0_586:
	s_add_u32 s22, s20, 0xfffc0080
	s_addc_u32 s23, s21, -1
	s_add_i32 s48, 0, 0x10000
	v_add_u32_e32 v140, s48, v143
	ds_read_b128 v[162:165], v140
	ds_read_b128 v[166:169], v140 offset:1024
	ds_read_b128 v[170:173], v140 offset:2048
	ds_read_b128 v[174:177], v140 offset:3072
	s_cmp_eq_u32 s47, 12
	s_cselect_b32 s25, s9, s23
	s_cselect_b32 s24, s43, s22
	s_cselect_b32 s23, s1, s46
	s_cselect_b32 s22, s44, s45
	v_lshl_add_u64 v[140:141], s[20:21], 0, v[136:137]
	s_add_i32 m0, s3, 0xc000
	ds_read_b128 v[178:181], v145
	ds_read_b128 v[182:185], v145 offset:1024
	ds_read_b128 v[206:209], v145 offset:2048
	ds_read_b128 v[210:213], v145 offset:3072
	ds_read_b128 v[214:217], v145 offset:4096
	ds_read_b128 v[218:221], v145 offset:5120
	ds_read_b128 v[222:225], v145 offset:6144
	ds_read_b128 v[226:229], v145 offset:7168
	global_load_lds_dwordx4 v[140:141], off
	s_add_i32 m0, s3, 0xe000
	s_nop 0
	global_load_lds_dwordx4 v138, s[20:21]
	s_waitcnt lgkmcnt(8)
	s_barrier
	s_waitcnt lgkmcnt(0)
	v_mfma_f32_16x16x32_bf16 v[122:125], v[162:165], v[178:181], v[122:125]
	v_mfma_f32_16x16x32_bf16 v[114:117], v[170:173], v[178:181], v[114:117]
	v_mfma_f32_16x16x32_bf16 v[106:109], v[162:165], v[206:209], v[106:109]
	v_mfma_f32_16x16x32_bf16 v[98:101], v[170:173], v[206:209], v[98:101]
	v_mfma_f32_16x16x32_bf16 v[90:93], v[162:165], v[214:217], v[90:93]
	v_mfma_f32_16x16x32_bf16 v[82:85], v[170:173], v[214:217], v[82:85]
	v_mfma_f32_16x16x32_bf16 v[74:77], v[162:165], v[222:225], v[74:77]
	v_mfma_f32_16x16x32_bf16 v[66:69], v[170:173], v[222:225], v[66:69]
	v_mfma_f32_16x16x32_bf16 v[122:125], v[166:169], v[182:185], v[122:125]
	v_mfma_f32_16x16x32_bf16 v[114:117], v[174:177], v[182:185], v[114:117]
	v_mfma_f32_16x16x32_bf16 v[106:109], v[166:169], v[210:213], v[106:109]
	v_mfma_f32_16x16x32_bf16 v[98:101], v[174:177], v[210:213], v[98:101]
	v_mfma_f32_16x16x32_bf16 v[90:93], v[166:169], v[218:221], v[90:93]
	v_mfma_f32_16x16x32_bf16 v[82:85], v[174:177], v[218:221], v[82:85]
	v_mfma_f32_16x16x32_bf16 v[74:77], v[166:169], v[226:229], v[74:77]
	v_mfma_f32_16x16x32_bf16 v[66:69], v[174:177], v[226:229], v[66:69]
	s_barrier
	s_add_i32 s50, 0, 0x14000
	v_add_u32_e32 v140, s50, v143
	s_add_i32 s48, s48, s29
	ds_read_b128 v[230:233], v140
	ds_read_b128 v[234:237], v140 offset:1024
	ds_read_b128 v[238:241], v140 offset:2048
	ds_read_b128 v[242:245], v140 offset:3072
	v_lshl_add_u64 v[140:141], s[22:23], 0, v[0:1]
	s_mov_b32 m0, s48
	v_lshl_add_u64 v[186:187], s[22:23], 0, v[130:131]
	global_load_lds_dwordx4 v[140:141], off
	s_add_i32 m0, s48, 0x2000
	s_nop 0
	global_load_lds_dwordx4 v[186:187], off
	s_barrier
	s_waitcnt lgkmcnt(0)
	v_mfma_f32_16x16x32_bf16 v[126:129], v[230:233], v[178:181], v[126:129]
	v_mfma_f32_16x16x32_bf16 v[118:121], v[238:241], v[178:181], v[118:121]
	v_mfma_f32_16x16x32_bf16 v[110:113], v[230:233], v[206:209], v[110:113]
	v_mfma_f32_16x16x32_bf16 v[102:105], v[238:241], v[206:209], v[102:105]
	v_mfma_f32_16x16x32_bf16 v[94:97], v[230:233], v[214:217], v[94:97]
	v_mfma_f32_16x16x32_bf16 v[86:89], v[238:241], v[214:217], v[86:89]
	v_mfma_f32_16x16x32_bf16 v[78:81], v[230:233], v[222:225], v[78:81]
	v_mfma_f32_16x16x32_bf16 v[70:73], v[238:241], v[222:225], v[70:73]
	v_mfma_f32_16x16x32_bf16 v[126:129], v[234:237], v[182:185], v[126:129]
	v_mfma_f32_16x16x32_bf16 v[118:121], v[242:245], v[182:185], v[118:121]
	v_mfma_f32_16x16x32_bf16 v[110:113], v[234:237], v[210:213], v[110:113]
	v_mfma_f32_16x16x32_bf16 v[102:105], v[242:245], v[210:213], v[102:105]
	v_mfma_f32_16x16x32_bf16 v[94:97], v[234:237], v[218:221], v[94:97]
	v_mfma_f32_16x16x32_bf16 v[86:89], v[242:245], v[218:221], v[86:89]
	v_mfma_f32_16x16x32_bf16 v[78:81], v[234:237], v[226:229], v[78:81]
	v_mfma_f32_16x16x32_bf16 v[70:73], v[242:245], v[226:229], v[70:73]
	s_barrier
	s_mov_b32 m0, s3
	v_lshl_add_u64 v[246:247], s[24:25], 0, v[134:135]
	ds_read_b128 v[178:181], v145 offset:16384
	ds_read_b128 v[182:185], v145 offset:17408
	ds_read_b128 v[206:209], v145 offset:18432
	ds_read_b128 v[210:213], v145 offset:19456
	ds_read_b128 v[214:217], v145 offset:20480
	ds_read_b128 v[218:221], v145 offset:21504
	ds_read_b128 v[222:225], v145 offset:22528
	ds_read_b128 v[226:229], v145 offset:23552
	global_load_lds_dwordx4 v[246:247], off
	s_mov_b32 m0, s31
	v_lshl_add_u64 v[248:249], s[24:25], 0, v[132:133]
	global_load_lds_dwordx4 v[248:249], off
	s_barrier
	s_waitcnt lgkmcnt(0)
	v_mfma_f32_16x16x32_bf16 v[58:61], v[162:165], v[178:181], v[58:61]
	v_mfma_f32_16x16x32_bf16 v[50:53], v[170:173], v[178:181], v[50:53]
	v_mfma_f32_16x16x32_bf16 v[42:45], v[162:165], v[206:209], v[42:45]
	v_mfma_f32_16x16x32_bf16 v[34:37], v[170:173], v[206:209], v[34:37]
	v_mfma_f32_16x16x32_bf16 v[26:29], v[162:165], v[214:217], v[26:29]
	v_mfma_f32_16x16x32_bf16 v[18:21], v[170:173], v[214:217], v[18:21]
	v_mfma_f32_16x16x32_bf16 v[10:13], v[162:165], v[222:225], v[10:13]
	v_mfma_f32_16x16x32_bf16 v[6:9], v[170:173], v[222:225], v[6:9]
	v_mfma_f32_16x16x32_bf16 v[58:61], v[166:169], v[182:185], v[58:61]
	v_mfma_f32_16x16x32_bf16 v[50:53], v[174:177], v[182:185], v[50:53]
	v_mfma_f32_16x16x32_bf16 v[42:45], v[166:169], v[210:213], v[42:45]
	v_mfma_f32_16x16x32_bf16 v[34:37], v[174:177], v[210:213], v[34:37]
	v_mfma_f32_16x16x32_bf16 v[26:29], v[166:169], v[218:221], v[26:29]
	v_mfma_f32_16x16x32_bf16 v[18:21], v[174:177], v[218:221], v[18:21]
	v_mfma_f32_16x16x32_bf16 v[10:13], v[166:169], v[226:229], v[10:13]
	v_mfma_f32_16x16x32_bf16 v[6:9], v[174:177], v[226:229], v[6:9]
	s_barrier
	s_add_u32 s48, s22, 0x40000
	s_addc_u32 s49, s23, 0
	s_add_i32 s50, s50, s29
	s_mov_b32 m0, s50
	s_nop 0
	global_load_lds_dwordx4 v0, s[48:49]
	s_add_i32 m0, s50, 0x2000
	s_nop 0
	global_load_lds_dwordx4 v130, s[48:49]
	s_waitcnt vmcnt(6)
	s_barrier
	v_mfma_f32_16x16x32_bf16 v[62:65], v[230:233], v[178:181], v[62:65]
	v_mfma_f32_16x16x32_bf16 v[54:57], v[238:241], v[178:181], v[54:57]
	v_mfma_f32_16x16x32_bf16 v[46:49], v[230:233], v[206:209], v[46:49]
	v_mfma_f32_16x16x32_bf16 v[38:41], v[238:241], v[206:209], v[38:41]
	v_mfma_f32_16x16x32_bf16 v[30:33], v[230:233], v[214:217], v[30:33]
	v_mfma_f32_16x16x32_bf16 v[22:25], v[238:241], v[214:217], v[22:25]
	v_mfma_f32_16x16x32_bf16 v[14:17], v[230:233], v[222:225], v[14:17]
	v_mfma_f32_16x16x32_bf16 v[2:5], v[238:241], v[222:225], v[2:5]
	v_mfma_f32_16x16x32_bf16 v[62:65], v[234:237], v[182:185], v[62:65]
	v_mfma_f32_16x16x32_bf16 v[54:57], v[242:245], v[182:185], v[54:57]
	v_mfma_f32_16x16x32_bf16 v[46:49], v[234:237], v[210:213], v[46:49]
	v_mfma_f32_16x16x32_bf16 v[38:41], v[242:245], v[210:213], v[38:41]
	v_mfma_f32_16x16x32_bf16 v[30:33], v[234:237], v[218:221], v[30:33]
	v_mfma_f32_16x16x32_bf16 v[22:25], v[242:245], v[218:221], v[22:25]
	v_mfma_f32_16x16x32_bf16 v[14:17], v[234:237], v[226:229], v[14:17]
	v_mfma_f32_16x16x32_bf16 v[2:5], v[242:245], v[226:229], v[2:5]
	s_barrier
	s_add_i32 s48, 0, 0x18000
	v_add_u32_e32 v174, s48, v143
	ds_read_b128 v[162:165], v174
	ds_read_b128 v[166:169], v174 offset:1024
	ds_read_b128 v[170:173], v174 offset:2048
	ds_read_b128 v[174:177], v174 offset:3072
	s_add_u32 s24, s24, 0x40000
	s_addc_u32 s25, s25, 0
	s_mov_b32 m0, s34
	v_lshl_add_u64 v[230:231], s[24:25], 0, v[134:135]
	ds_read_b128 v[178:181], v145 offset:32768
	ds_read_b128 v[182:185], v145 offset:33792
	ds_read_b128 v[206:209], v145 offset:34816
	ds_read_b128 v[210:213], v145 offset:35840
	ds_read_b128 v[214:217], v145 offset:36864
	ds_read_b128 v[218:221], v145 offset:37888
	ds_read_b128 v[222:225], v145 offset:38912
	ds_read_b128 v[226:229], v145 offset:39936
	global_load_lds_dwordx4 v[230:231], off
	s_mov_b32 m0, s35
	s_nop 0
	global_load_lds_dwordx4 v132, s[24:25]
	s_waitcnt lgkmcnt(8)
	s_barrier
	s_waitcnt lgkmcnt(0)
	v_mfma_f32_16x16x32_bf16 v[122:125], v[162:165], v[178:181], v[122:125]
	v_mfma_f32_16x16x32_bf16 v[114:117], v[170:173], v[178:181], v[114:117]
	v_mfma_f32_16x16x32_bf16 v[106:109], v[162:165], v[206:209], v[106:109]
	v_mfma_f32_16x16x32_bf16 v[98:101], v[170:173], v[206:209], v[98:101]
	v_mfma_f32_16x16x32_bf16 v[90:93], v[162:165], v[214:217], v[90:93]
	v_mfma_f32_16x16x32_bf16 v[82:85], v[170:173], v[214:217], v[82:85]
	v_mfma_f32_16x16x32_bf16 v[74:77], v[162:165], v[222:225], v[74:77]
	v_mfma_f32_16x16x32_bf16 v[66:69], v[170:173], v[222:225], v[66:69]
	v_mfma_f32_16x16x32_bf16 v[122:125], v[166:169], v[182:185], v[122:125]
	v_mfma_f32_16x16x32_bf16 v[114:117], v[174:177], v[182:185], v[114:117]
	v_mfma_f32_16x16x32_bf16 v[106:109], v[166:169], v[210:213], v[106:109]
	v_mfma_f32_16x16x32_bf16 v[98:101], v[174:177], v[210:213], v[98:101]
	v_mfma_f32_16x16x32_bf16 v[90:93], v[166:169], v[218:221], v[90:93]
	v_mfma_f32_16x16x32_bf16 v[82:85], v[174:177], v[218:221], v[82:85]
	v_mfma_f32_16x16x32_bf16 v[74:77], v[166:169], v[226:229], v[74:77]
	v_mfma_f32_16x16x32_bf16 v[66:69], v[174:177], v[226:229], v[66:69]
	s_barrier
	s_add_i32 s24, 0, 0x1c000
	s_add_i32 s25, s48, s29
	v_add_u32_e32 v205, s24, v143
	v_lshl_add_u64 v[140:141], v[140:141], 0, s[94:95]
	s_mov_b32 m0, s25
	ds_read_b128 v[230:233], v205
	ds_read_b128 v[234:237], v205 offset:1024
	ds_read_b128 v[238:241], v205 offset:2048
	ds_read_b128 v[242:245], v205 offset:3072
	global_load_lds_dwordx4 v[140:141], off
	s_add_i32 m0, s25, 0x2000
	v_lshl_add_u64 v[140:141], v[186:187], 0, s[94:95]
	global_load_lds_dwordx4 v[140:141], off
	s_barrier
	s_waitcnt lgkmcnt(0)
	v_mfma_f32_16x16x32_bf16 v[126:129], v[230:233], v[178:181], v[126:129]
	v_mfma_f32_16x16x32_bf16 v[118:121], v[238:241], v[178:181], v[118:121]
	v_mfma_f32_16x16x32_bf16 v[110:113], v[230:233], v[206:209], v[110:113]
	v_mfma_f32_16x16x32_bf16 v[102:105], v[238:241], v[206:209], v[102:105]
	v_mfma_f32_16x16x32_bf16 v[94:97], v[230:233], v[214:217], v[94:97]
	v_mfma_f32_16x16x32_bf16 v[86:89], v[238:241], v[214:217], v[86:89]
	v_mfma_f32_16x16x32_bf16 v[78:81], v[230:233], v[222:225], v[78:81]
	v_mfma_f32_16x16x32_bf16 v[70:73], v[238:241], v[222:225], v[70:73]
	v_mfma_f32_16x16x32_bf16 v[126:129], v[234:237], v[182:185], v[126:129]
	v_mfma_f32_16x16x32_bf16 v[118:121], v[242:245], v[182:185], v[118:121]
	v_mfma_f32_16x16x32_bf16 v[110:113], v[234:237], v[210:213], v[110:113]
	v_mfma_f32_16x16x32_bf16 v[102:105], v[242:245], v[210:213], v[102:105]
	v_mfma_f32_16x16x32_bf16 v[94:97], v[234:237], v[218:221], v[94:97]
	v_mfma_f32_16x16x32_bf16 v[86:89], v[242:245], v[218:221], v[86:89]
	v_mfma_f32_16x16x32_bf16 v[78:81], v[234:237], v[226:229], v[78:81]
	v_mfma_f32_16x16x32_bf16 v[70:73], v[242:245], v[226:229], v[70:73]
	s_barrier
	s_mov_b32 m0, s37
	v_lshl_add_u64 v[140:141], v[246:247], 0, s[94:95]
	ds_read_b128 v[178:181], v145 offset:49152
	ds_read_b128 v[182:185], v145 offset:50176
	ds_read_b128 v[206:209], v145 offset:51200
	ds_read_b128 v[210:213], v145 offset:52224
	ds_read_b128 v[214:217], v145 offset:53248
	ds_read_b128 v[218:221], v145 offset:54272
	ds_read_b128 v[222:225], v145 offset:55296
	ds_read_b128 v[226:229], v145 offset:56320
	global_load_lds_dwordx4 v[140:141], off
	s_mov_b32 m0, s40
	v_lshl_add_u64 v[140:141], v[248:249], 0, s[94:95]
	global_load_lds_dwordx4 v[140:141], off
	s_barrier
	s_waitcnt lgkmcnt(0)
	v_mfma_f32_16x16x32_bf16 v[58:61], v[162:165], v[178:181], v[58:61]
	v_mfma_f32_16x16x32_bf16 v[50:53], v[170:173], v[178:181], v[50:53]
	v_mfma_f32_16x16x32_bf16 v[42:45], v[162:165], v[206:209], v[42:45]
	v_mfma_f32_16x16x32_bf16 v[34:37], v[170:173], v[206:209], v[34:37]
	v_mfma_f32_16x16x32_bf16 v[26:29], v[162:165], v[214:217], v[26:29]
	v_mfma_f32_16x16x32_bf16 v[18:21], v[170:173], v[214:217], v[18:21]
	v_mfma_f32_16x16x32_bf16 v[10:13], v[162:165], v[222:225], v[10:13]
	v_mfma_f32_16x16x32_bf16 v[6:9], v[170:173], v[222:225], v[6:9]
	v_mfma_f32_16x16x32_bf16 v[58:61], v[166:169], v[182:185], v[58:61]
	v_mfma_f32_16x16x32_bf16 v[50:53], v[174:177], v[182:185], v[50:53]
	v_mfma_f32_16x16x32_bf16 v[42:45], v[166:169], v[210:213], v[42:45]
	v_mfma_f32_16x16x32_bf16 v[34:37], v[174:177], v[210:213], v[34:37]
	v_mfma_f32_16x16x32_bf16 v[26:29], v[166:169], v[218:221], v[26:29]
	v_mfma_f32_16x16x32_bf16 v[18:21], v[174:177], v[218:221], v[18:21]
	v_mfma_f32_16x16x32_bf16 v[10:13], v[166:169], v[226:229], v[10:13]
	v_mfma_f32_16x16x32_bf16 v[6:9], v[174:177], v[226:229], v[6:9]
	s_barrier
	s_add_u32 s22, s22, 0x40080
	s_addc_u32 s23, s23, 0
	s_add_i32 s24, s24, s29
	s_mov_b32 m0, s24
	s_nop 0
	global_load_lds_dwordx4 v0, s[22:23]
	s_add_i32 m0, s24, 0x2000
	s_nop 0
	global_load_lds_dwordx4 v130, s[22:23]
	s_waitcnt vmcnt(6)
	s_barrier
	v_mfma_f32_16x16x32_bf16 v[62:65], v[230:233], v[178:181], v[62:65]
	v_mfma_f32_16x16x32_bf16 v[54:57], v[238:241], v[178:181], v[54:57]
	v_mfma_f32_16x16x32_bf16 v[46:49], v[230:233], v[206:209], v[46:49]
	v_mfma_f32_16x16x32_bf16 v[38:41], v[238:241], v[206:209], v[38:41]
	v_mfma_f32_16x16x32_bf16 v[30:33], v[230:233], v[214:217], v[30:33]
	v_mfma_f32_16x16x32_bf16 v[22:25], v[238:241], v[214:217], v[22:25]
	v_mfma_f32_16x16x32_bf16 v[14:17], v[230:233], v[222:225], v[14:17]
	v_mfma_f32_16x16x32_bf16 v[2:5], v[238:241], v[222:225], v[2:5]
	v_mfma_f32_16x16x32_bf16 v[62:65], v[234:237], v[182:185], v[62:65]
	v_mfma_f32_16x16x32_bf16 v[54:57], v[242:245], v[182:185], v[54:57]
	v_mfma_f32_16x16x32_bf16 v[46:49], v[234:237], v[210:213], v[46:49]
	v_mfma_f32_16x16x32_bf16 v[38:41], v[242:245], v[210:213], v[38:41]
	v_mfma_f32_16x16x32_bf16 v[30:33], v[234:237], v[218:221], v[30:33]
	v_mfma_f32_16x16x32_bf16 v[22:25], v[242:245], v[218:221], v[22:25]
	v_mfma_f32_16x16x32_bf16 v[14:17], v[234:237], v[226:229], v[14:17]
	v_mfma_f32_16x16x32_bf16 v[2:5], v[242:245], v[226:229], v[2:5]
	s_barrier
	s_add_i32 s47, s47, 2
	s_add_u32 s20, s20, 0x100
	s_addc_u32 s21, s21, 0
	s_add_u32 s45, s45, 0x100
	s_addc_u32 s46, s46, 0
	s_cmp_gt_u32 s47, 13
	s_cbranch_scc0 .LBB0_586
	v_pk_mul_f32 v[164:165], v[122:123], s[4:5] op_sel_hi:[1,0]
	v_pk_mul_f32 v[122:123], v[122:123], v[126:127]
	v_pk_mul_f32 v[126:127], v[114:115], s[4:5] op_sel_hi:[1,0]
	v_pk_mul_f32 v[114:115], v[114:115], v[118:119]
	v_exp_f32_e32 v126, v126
	v_exp_f32_e32 v127, v127
	v_pk_mul_f32 v[128:129], v[124:125], v[128:129]
	v_pk_mul_f32 v[124:125], v[124:125], s[4:5] op_sel_hi:[1,0]
	v_exp_f32_e32 v164, v164
	v_pk_add_f32 v[126:127], v[126:127], 1.0 op_sel_hi:[1,0]
	v_exp_f32_e32 v165, v165
	v_rcp_f32_e32 v126, v126
	v_rcp_f32_e32 v127, v127
	v_exp_f32_e32 v124, v124
	v_exp_f32_e32 v125, v125
	v_pk_add_f32 v[164:165], v[164:165], 1.0 op_sel_hi:[1,0]
	v_pk_mul_f32 v[118:119], v[126:127], v[114:115]
	v_pk_mul_f32 v[114:115], v[116:117], s[4:5] op_sel_hi:[1,0]
	v_pk_add_f32 v[124:125], v[124:125], 1.0 op_sel_hi:[1,0]
	v_exp_f32_e32 v114, v114
	v_exp_f32_e32 v115, v115
	v_rcp_f32_e32 v164, v164
	v_rcp_f32_e32 v165, v165
	v_rcp_f32_e32 v124, v124
	v_pk_add_f32 v[114:115], v[114:115], 1.0 op_sel_hi:[1,0]
	v_rcp_f32_e32 v125, v125
	v_rcp_f32_e32 v114, v114
	v_rcp_f32_e32 v115, v115
	v_lshl_or_b32 v140, s42, 7, v144
	v_ashrrev_i32_e32 v141, 31, v140
	v_lshl_add_u32 v162, s2, 8, v142
	v_lshl_add_u64 v[140:141], v[140:141], 1, s[14:15]
	v_pk_mul_f32 v[120:121], v[116:117], v[120:121]
	v_pk_mul_f32 v[122:123], v[164:165], v[122:123]
	v_pk_mul_f32 v[124:125], v[124:125], v[128:129]
	v_pk_mul_f32 v[120:121], v[114:115], v[120:121]
	v_mad_i64_i32 v[126:127], s[20:21], v162, s91, v[140:141]
	v_cvt_pk_bf16_f32 v114, v122, v123
	v_cvt_pk_bf16_f32 v115, v124, v125
	v_cvt_pk_bf16_f32 v116, v118, v119
	v_cvt_pk_bf16_f32 v117, v120, v121
	global_store_dwordx4 v[126:127], v[114:117], off
	v_pk_mul_f32 v[112:113], v[108:109], v[112:113]
	v_pk_mul_f32 v[108:109], v[108:109], s[4:5] op_sel_hi:[1,0]
	v_pk_mul_f32 v[114:115], v[106:107], s[4:5] op_sel_hi:[1,0]
	v_pk_mul_f32 v[106:107], v[106:107], v[110:111]
	v_pk_mul_f32 v[110:111], v[98:99], s[4:5] op_sel_hi:[1,0]
	v_pk_mul_f32 v[98:99], v[98:99], v[102:103]
	v_exp_f32_e32 v110, v110
	v_exp_f32_e32 v111, v111
	v_exp_f32_e32 v114, v114
	v_exp_f32_e32 v115, v115
	v_exp_f32_e32 v108, v108
	v_pk_add_f32 v[110:111], v[110:111], 1.0 op_sel_hi:[1,0]
	v_exp_f32_e32 v109, v109
	v_rcp_f32_e32 v110, v110
	v_rcp_f32_e32 v111, v111
	v_pk_add_f32 v[114:115], v[114:115], 1.0 op_sel_hi:[1,0]
	v_pk_add_f32 v[108:109], v[108:109], 1.0 op_sel_hi:[1,0]
	v_rcp_f32_e32 v114, v114
	v_pk_mul_f32 v[102:103], v[110:111], v[98:99]
	v_pk_mul_f32 v[98:99], v[100:101], s[4:5] op_sel_hi:[1,0]
	v_rcp_f32_e32 v115, v115
	v_exp_f32_e32 v98, v98
	v_exp_f32_e32 v99, v99
	v_rcp_f32_e32 v108, v108
	v_rcp_f32_e32 v109, v109
	v_or_b32_e32 v116, 16, v162
	v_pk_add_f32 v[98:99], v[98:99], 1.0 op_sel_hi:[1,0]
	v_pk_mul_f32 v[104:105], v[100:101], v[104:105]
	v_rcp_f32_e32 v98, v98
	v_rcp_f32_e32 v99, v99
	v_pk_mul_f32 v[106:107], v[114:115], v[106:107]
	v_pk_mul_f32 v[108:109], v[108:109], v[112:113]
	v_mad_i64_i32 v[110:111], s[20:21], v116, s91, v[140:141]
	v_pk_mul_f32 v[104:105], v[98:99], v[104:105]
	v_cvt_pk_bf16_f32 v98, v106, v107
	v_cvt_pk_bf16_f32 v99, v108, v109
	v_cvt_pk_bf16_f32 v100, v102, v103
	v_pk_mul_f32 v[96:97], v[92:93], v[96:97]
	v_cvt_pk_bf16_f32 v101, v104, v105
	global_store_dwordx4 v[110:111], v[98:101], off
	v_pk_mul_f32 v[92:93], v[92:93], s[4:5] op_sel_hi:[1,0]
	v_pk_mul_f32 v[88:89], v[84:85], v[88:89]
	v_pk_mul_f32 v[98:99], v[90:91], s[4:5] op_sel_hi:[1,0]
	v_pk_mul_f32 v[90:91], v[90:91], v[94:95]
	v_pk_mul_f32 v[94:95], v[82:83], s[4:5] op_sel_hi:[1,0]
	v_pk_mul_f32 v[82:83], v[82:83], v[86:87]
	v_exp_f32_e32 v94, v94
	v_exp_f32_e32 v95, v95
	v_exp_f32_e32 v98, v98
	v_exp_f32_e32 v99, v99
	v_exp_f32_e32 v92, v92
	v_pk_add_f32 v[94:95], v[94:95], 1.0 op_sel_hi:[1,0]
	v_exp_f32_e32 v93, v93
	v_rcp_f32_e32 v94, v94
	v_rcp_f32_e32 v95, v95
	v_pk_add_f32 v[98:99], v[98:99], 1.0 op_sel_hi:[1,0]
	v_pk_add_f32 v[92:93], v[92:93], 1.0 op_sel_hi:[1,0]
	v_rcp_f32_e32 v98, v98
	v_pk_mul_f32 v[86:87], v[94:95], v[82:83]
	v_pk_mul_f32 v[82:83], v[84:85], s[4:5] op_sel_hi:[1,0]
	v_rcp_f32_e32 v99, v99
	v_exp_f32_e32 v82, v82
	v_exp_f32_e32 v83, v83
	v_rcp_f32_e32 v92, v92
	v_rcp_f32_e32 v93, v93
	v_or_b32_e32 v100, 32, v162
	v_pk_add_f32 v[82:83], v[82:83], 1.0 op_sel_hi:[1,0]
	v_pk_mul_f32 v[90:91], v[98:99], v[90:91]
	v_rcp_f32_e32 v82, v82
	v_rcp_f32_e32 v83, v83
	v_pk_mul_f32 v[92:93], v[92:93], v[96:97]
	v_mad_i64_i32 v[94:95], s[20:21], v100, s91, v[140:141]
	v_pk_mul_f32 v[88:89], v[82:83], v[88:89]
	v_cvt_pk_bf16_f32 v82, v90, v91
	v_cvt_pk_bf16_f32 v83, v92, v93
	v_cvt_pk_bf16_f32 v84, v86, v87
	v_pk_mul_f32 v[80:81], v[76:77], v[80:81]
	v_cvt_pk_bf16_f32 v85, v88, v89
	global_store_dwordx4 v[94:95], v[82:85], off
	v_pk_mul_f32 v[76:77], v[76:77], s[4:5] op_sel_hi:[1,0]
	v_pk_mul_f32 v[72:73], v[68:69], v[72:73]
	v_pk_mul_f32 v[82:83], v[74:75], s[4:5] op_sel_hi:[1,0]
	v_pk_mul_f32 v[74:75], v[74:75], v[78:79]
	v_pk_mul_f32 v[78:79], v[66:67], s[4:5] op_sel_hi:[1,0]
	v_pk_mul_f32 v[66:67], v[66:67], v[70:71]
	v_exp_f32_e32 v78, v78
	v_exp_f32_e32 v79, v79
	v_exp_f32_e32 v82, v82
	v_exp_f32_e32 v83, v83
	v_exp_f32_e32 v76, v76
	v_pk_add_f32 v[78:79], v[78:79], 1.0 op_sel_hi:[1,0]
	v_exp_f32_e32 v77, v77
	v_rcp_f32_e32 v78, v78
	v_rcp_f32_e32 v79, v79
	v_pk_add_f32 v[82:83], v[82:83], 1.0 op_sel_hi:[1,0]
	v_pk_add_f32 v[76:77], v[76:77], 1.0 op_sel_hi:[1,0]
	v_rcp_f32_e32 v82, v82
	v_pk_mul_f32 v[70:71], v[78:79], v[66:67]
	v_pk_mul_f32 v[66:67], v[68:69], s[4:5] op_sel_hi:[1,0]
	v_rcp_f32_e32 v83, v83
	v_exp_f32_e32 v66, v66
	v_exp_f32_e32 v67, v67
	v_rcp_f32_e32 v76, v76
	v_rcp_f32_e32 v77, v77
	v_or_b32_e32 v84, 48, v162
	v_pk_add_f32 v[66:67], v[66:67], 1.0 op_sel_hi:[1,0]
	v_pk_mul_f32 v[74:75], v[82:83], v[74:75]
	v_rcp_f32_e32 v66, v66
	v_rcp_f32_e32 v67, v67
	v_pk_mul_f32 v[76:77], v[76:77], v[80:81]
	v_mad_i64_i32 v[78:79], s[20:21], v84, s91, v[140:141]
	v_pk_mul_f32 v[72:73], v[66:67], v[72:73]
	v_cvt_pk_bf16_f32 v66, v74, v75
	v_cvt_pk_bf16_f32 v67, v76, v77
	v_cvt_pk_bf16_f32 v68, v70, v71
	v_pk_mul_f32 v[64:65], v[60:61], v[64:65]
	v_cvt_pk_bf16_f32 v69, v72, v73
	global_store_dwordx4 v[78:79], v[66:69], off
	v_pk_mul_f32 v[60:61], v[60:61], s[4:5] op_sel_hi:[1,0]
	v_pk_mul_f32 v[56:57], v[52:53], v[56:57]
	v_pk_mul_f32 v[66:67], v[58:59], s[4:5] op_sel_hi:[1,0]
	v_pk_mul_f32 v[58:59], v[58:59], v[62:63]
	v_pk_mul_f32 v[62:63], v[50:51], s[4:5] op_sel_hi:[1,0]
	v_pk_mul_f32 v[50:51], v[50:51], v[54:55]
	v_exp_f32_e32 v62, v62
	v_exp_f32_e32 v63, v63
	v_exp_f32_e32 v66, v66
	v_exp_f32_e32 v67, v67
	v_exp_f32_e32 v60, v60
	v_pk_add_f32 v[62:63], v[62:63], 1.0 op_sel_hi:[1,0]
	v_exp_f32_e32 v61, v61
	v_rcp_f32_e32 v62, v62
	v_rcp_f32_e32 v63, v63
	v_pk_add_f32 v[66:67], v[66:67], 1.0 op_sel_hi:[1,0]
	v_pk_add_f32 v[60:61], v[60:61], 1.0 op_sel_hi:[1,0]
	v_rcp_f32_e32 v66, v66
	v_pk_mul_f32 v[54:55], v[62:63], v[50:51]
	v_pk_mul_f32 v[50:51], v[52:53], s[4:5] op_sel_hi:[1,0]
	v_rcp_f32_e32 v67, v67
	v_exp_f32_e32 v50, v50
	v_exp_f32_e32 v51, v51
	v_rcp_f32_e32 v60, v60
	v_rcp_f32_e32 v61, v61
	v_add_u32_e32 v68, 0x80, v162
	v_pk_add_f32 v[50:51], v[50:51], 1.0 op_sel_hi:[1,0]
	v_pk_mul_f32 v[58:59], v[66:67], v[58:59]
	v_rcp_f32_e32 v50, v50
	v_rcp_f32_e32 v51, v51
	v_pk_mul_f32 v[60:61], v[60:61], v[64:65]
	v_mad_i64_i32 v[62:63], s[20:21], v68, s91, v[140:141]
	v_pk_mul_f32 v[56:57], v[50:51], v[56:57]
	v_cvt_pk_bf16_f32 v50, v58, v59
	v_cvt_pk_bf16_f32 v51, v60, v61
	v_cvt_pk_bf16_f32 v52, v54, v55
	v_pk_mul_f32 v[48:49], v[44:45], v[48:49]
	v_cvt_pk_bf16_f32 v53, v56, v57
	global_store_dwordx4 v[62:63], v[50:53], off
	v_pk_mul_f32 v[44:45], v[44:45], s[4:5] op_sel_hi:[1,0]
	v_pk_mul_f32 v[40:41], v[36:37], v[40:41]
	v_pk_mul_f32 v[50:51], v[42:43], s[4:5] op_sel_hi:[1,0]
	v_pk_mul_f32 v[42:43], v[42:43], v[46:47]
	v_pk_mul_f32 v[46:47], v[34:35], s[4:5] op_sel_hi:[1,0]
	v_pk_mul_f32 v[34:35], v[34:35], v[38:39]
	v_exp_f32_e32 v46, v46
	v_exp_f32_e32 v47, v47
	v_exp_f32_e32 v50, v50
	v_exp_f32_e32 v51, v51
	v_exp_f32_e32 v44, v44
	v_pk_add_f32 v[46:47], v[46:47], 1.0 op_sel_hi:[1,0]
	v_exp_f32_e32 v45, v45
	v_rcp_f32_e32 v46, v46
	v_rcp_f32_e32 v47, v47
	v_pk_add_f32 v[50:51], v[50:51], 1.0 op_sel_hi:[1,0]
	v_pk_add_f32 v[44:45], v[44:45], 1.0 op_sel_hi:[1,0]
	v_rcp_f32_e32 v50, v50
	v_pk_mul_f32 v[38:39], v[46:47], v[34:35]
	v_pk_mul_f32 v[34:35], v[36:37], s[4:5] op_sel_hi:[1,0]
	v_rcp_f32_e32 v51, v51
	v_exp_f32_e32 v34, v34
	v_exp_f32_e32 v35, v35
	v_rcp_f32_e32 v44, v44
	v_rcp_f32_e32 v45, v45
	v_add_u32_e32 v52, 0x90, v162
	v_pk_add_f32 v[34:35], v[34:35], 1.0 op_sel_hi:[1,0]
	v_pk_mul_f32 v[42:43], v[50:51], v[42:43]
	v_rcp_f32_e32 v34, v34
	v_rcp_f32_e32 v35, v35
	v_pk_mul_f32 v[44:45], v[44:45], v[48:49]
	v_mad_i64_i32 v[46:47], s[20:21], v52, s91, v[140:141]
	v_pk_mul_f32 v[40:41], v[34:35], v[40:41]
	v_cvt_pk_bf16_f32 v34, v42, v43
	v_cvt_pk_bf16_f32 v35, v44, v45
	v_cvt_pk_bf16_f32 v36, v38, v39
	v_pk_mul_f32 v[32:33], v[28:29], v[32:33]
	v_cvt_pk_bf16_f32 v37, v40, v41
	global_store_dwordx4 v[46:47], v[34:37], off
	v_pk_mul_f32 v[28:29], v[28:29], s[4:5] op_sel_hi:[1,0]
	v_pk_mul_f32 v[24:25], v[20:21], v[24:25]
	v_pk_mul_f32 v[34:35], v[26:27], s[4:5] op_sel_hi:[1,0]
	v_pk_mul_f32 v[26:27], v[26:27], v[30:31]
	v_pk_mul_f32 v[30:31], v[18:19], s[4:5] op_sel_hi:[1,0]
	v_pk_mul_f32 v[18:19], v[18:19], v[22:23]
	v_exp_f32_e32 v30, v30
	v_exp_f32_e32 v31, v31
	v_exp_f32_e32 v34, v34
	v_exp_f32_e32 v35, v35
	v_exp_f32_e32 v28, v28
	v_pk_add_f32 v[30:31], v[30:31], 1.0 op_sel_hi:[1,0]
	v_exp_f32_e32 v29, v29
	v_rcp_f32_e32 v30, v30
	v_rcp_f32_e32 v31, v31
	v_pk_add_f32 v[34:35], v[34:35], 1.0 op_sel_hi:[1,0]
	v_pk_add_f32 v[28:29], v[28:29], 1.0 op_sel_hi:[1,0]
	v_rcp_f32_e32 v34, v34
	v_pk_mul_f32 v[22:23], v[30:31], v[18:19]
	v_pk_mul_f32 v[18:19], v[20:21], s[4:5] op_sel_hi:[1,0]
	v_rcp_f32_e32 v35, v35
	v_exp_f32_e32 v18, v18
	v_exp_f32_e32 v19, v19
	v_rcp_f32_e32 v28, v28
	v_rcp_f32_e32 v29, v29
	v_add_u32_e32 v36, 0xa0, v162
	v_pk_add_f32 v[18:19], v[18:19], 1.0 op_sel_hi:[1,0]
	v_pk_mul_f32 v[26:27], v[34:35], v[26:27]
	v_rcp_f32_e32 v18, v18
	v_rcp_f32_e32 v19, v19
	v_pk_mul_f32 v[28:29], v[28:29], v[32:33]
	v_mad_i64_i32 v[30:31], s[20:21], v36, s91, v[140:141]
	v_pk_mul_f32 v[24:25], v[18:19], v[24:25]
	v_cvt_pk_bf16_f32 v18, v26, v27
	v_cvt_pk_bf16_f32 v19, v28, v29
	v_cvt_pk_bf16_f32 v20, v22, v23
	v_pk_mul_f32 v[2:3], v[6:7], v[2:3]
	v_cvt_pk_bf16_f32 v21, v24, v25
	global_store_dwordx4 v[30:31], v[18:21], off
	v_pk_mul_f32 v[16:17], v[12:13], v[16:17]
	v_pk_mul_f32 v[12:13], v[12:13], s[4:5] op_sel_hi:[1,0]
	v_pk_mul_f32 v[18:19], v[10:11], s[4:5] op_sel_hi:[1,0]
	v_pk_mul_f32 v[10:11], v[10:11], v[14:15]
	v_pk_mul_f32 v[14:15], v[6:7], s[4:5] op_sel_hi:[1,0]
	v_exp_f32_e32 v18, v18
	v_exp_f32_e32 v14, v14
	v_exp_f32_e32 v15, v15
	v_exp_f32_e32 v19, v19
	v_exp_f32_e32 v12, v12
	v_exp_f32_e32 v13, v13
	v_pk_add_f32 v[14:15], v[14:15], 1.0 op_sel_hi:[1,0]
	v_pk_add_f32 v[18:19], v[18:19], 1.0 op_sel_hi:[1,0]
	v_rcp_f32_e32 v14, v14
	v_rcp_f32_e32 v15, v15
	v_pk_add_f32 v[12:13], v[12:13], 1.0 op_sel_hi:[1,0]
	v_rcp_f32_e32 v18, v18
	v_rcp_f32_e32 v19, v19
	v_pk_mul_f32 v[6:7], v[14:15], v[2:3]
	v_pk_mul_f32 v[2:3], v[8:9], s[4:5] op_sel_hi:[1,0]
	v_rcp_f32_e32 v12, v12
	v_exp_f32_e32 v2, v2
	v_exp_f32_e32 v3, v3
	v_rcp_f32_e32 v13, v13
	v_add_u32_e32 v20, 0xb0, v162
	v_mad_i64_i32 v[14:15], s[20:21], v20, s91, v[140:141]
	v_pk_add_f32 v[2:3], v[2:3], 1.0 op_sel_hi:[1,0]
	v_pk_mul_f32 v[4:5], v[8:9], v[4:5]
	v_rcp_f32_e32 v2, v2
	v_rcp_f32_e32 v3, v3
	s_and_b64 vcc, exec, s[38:39]
	s_mov_b32 s42, s0
	s_mov_b32 s2, s8
	s_mov_b64 s[22:23], s[18:19]
	s_mov_b64 s[20:21], s[16:17]
	v_pk_mul_f32 v[10:11], v[18:19], v[10:11]
	v_pk_mul_f32 v[12:13], v[12:13], v[16:17]
	v_pk_mul_f32 v[8:9], v[2:3], v[4:5]
	v_cvt_pk_bf16_f32 v2, v10, v11
	v_cvt_pk_bf16_f32 v3, v12, v13
	v_cvt_pk_bf16_f32 v4, v6, v7
	s_nop 0
	v_cvt_pk_bf16_f32 v5, v8, v9
	global_store_dwordx4 v[14:15], v[2:5], off
	s_cbranch_vccz .LBB0_579
	s_waitcnt vmcnt(0)
	s_cmpk_gt_u32 s26, 0xff
	s_cbranch_scc1 .LBB0_590
	s_barrier
